# K-loop labels aligned to 64 bytes (code placement) on v21
# baseline (speedup 1.0000x reference)
.LBB0_132:
	s_ashr_i32 s25, s24, 31
	s_lshl_b64 s[28:29], s[24:25], 20
	v_readlane_b32 s25, v254, 62
	s_add_u32 s28, s25, s28
	v_readlane_b32 s25, v254, 63
	s_addc_u32 s29, s25, s29
	s_and_b64 s[4:5], s[4:5], exec
	s_cselect_b32 s25, s29, s31
	s_cselect_b32 s37, s28, s30
	s_add_u32 s50, s30, 0x100
	s_addc_u32 s51, s31, 0
	s_mov_b32 s57, -2
	s_add_u32 vcc_lo, s0, 0xffffc000
	s_addc_u32 vcc_hi, s1, -1
	s_mov_b32 m0, s52
	s_nop 0
	global_load_lds_dwordx4 v158, vcc
	s_mov_b32 m0, s53
	s_nop 0
	global_load_lds_dwordx4 v160, vcc
	ds_read_b128 v[130:133], v224
	ds_read_b128 v[134:137], v224 offset:1024
	ds_read_b128 v[138:141], v224 offset:2048
	ds_read_b128 v[142:145], v224 offset:3072
	ds_read_b128 v[146:149], v224 offset:16384
	ds_read_b128 v[162:165], v224 offset:17408
	ds_read_b128 v[166:169], v224 offset:18432
	ds_read_b128 v[170:173], v224 offset:19456
	ds_read_b128 v[174:177], v225
	ds_read_b128 v[178:181], v225 offset:1024
	ds_read_b128 v[182:185], v225 offset:2048
	ds_read_b128 v[186:189], v225 offset:3072
	ds_read_b128 v[190:193], v225 offset:4096
	ds_read_b128 v[204:207], v225 offset:5120
	ds_read_b128 v[208:211], v225 offset:6144
	ds_read_b128 v[212:215], v225 offset:7168
	s_add_u32 s4, s0, 0x100
	s_addc_u32 s5, s1, 0
	s_add_i32 s58, 0, 0x10000
	s_cmp_eq_u32 s57, 28
	s_cselect_b32 s35, s27, s5
	s_cselect_b32 s34, s26, s4
	s_cselect_b32 s31, s25, s51
	s_cselect_b32 s30, s37, s50
	s_add_i32 s59, 0, 0x14000
	s_add_i32 m0, s38, 0xc000
	s_nop 0
	global_load_lds_dwordx4 v158, s[0:1]
	s_add_i32 m0, s38, 0xe000
	s_nop 0
	global_load_lds_dwordx4 v160, s[0:1]
	s_waitcnt vmcnt(8)
	s_waitcnt lgkmcnt(0)
	v_mfma_f32_16x16x32_bf16 v[126:129], v[130:133], v[174:177], 0
	v_mfma_f32_16x16x32_bf16 v[126:129], v[134:137], v[178:181], v[126:129]
	s_barrier
	s_setprio 1
	v_mfma_f32_16x16x32_bf16 v[122:125], v[142:145], v[178:181], 0
	v_mfma_f32_16x16x32_bf16 v[122:125], v[138:141], v[174:177], v[122:125]
	v_mfma_f32_16x16x32_bf16 v[106:109], v[138:141], v[182:185], 0
	v_mfma_f32_16x16x32_bf16 v[106:109], v[142:145], v[186:189], v[106:109]
	v_mfma_f32_16x16x32_bf16 v[110:113], v[134:137], v[186:189], 0
	v_mfma_f32_16x16x32_bf16 v[110:113], v[130:133], v[182:185], v[110:113]
	v_mfma_f32_16x16x32_bf16 v[94:97], v[130:133], v[190:193], 0
	v_mfma_f32_16x16x32_bf16 v[94:97], v[134:137], v[204:207], v[94:97]
	v_mfma_f32_16x16x32_bf16 v[90:93], v[142:145], v[204:207], 0
	v_mfma_f32_16x16x32_bf16 v[90:93], v[138:141], v[190:193], v[90:93]
	v_mfma_f32_16x16x32_bf16 v[74:77], v[138:141], v[208:211], 0
	v_mfma_f32_16x16x32_bf16 v[74:77], v[142:145], v[212:215], v[74:77]
	v_mfma_f32_16x16x32_bf16 v[78:81], v[134:137], v[212:215], 0
	v_mfma_f32_16x16x32_bf16 v[78:81], v[130:133], v[208:211], v[78:81]
	v_mfma_f32_16x16x32_bf16 v[118:121], v[146:149], v[174:177], 0
	v_mfma_f32_16x16x32_bf16 v[118:121], v[162:165], v[178:181], v[118:121]
	v_mfma_f32_16x16x32_bf16 v[114:117], v[170:173], v[178:181], 0
	v_mfma_f32_16x16x32_bf16 v[114:117], v[166:169], v[174:177], v[114:117]
	v_mfma_f32_16x16x32_bf16 v[98:101], v[166:169], v[182:185], 0
	v_mfma_f32_16x16x32_bf16 v[98:101], v[170:173], v[186:189], v[98:101]
	v_mfma_f32_16x16x32_bf16 v[102:105], v[162:165], v[186:189], 0
	v_mfma_f32_16x16x32_bf16 v[102:105], v[146:149], v[182:185], v[102:105]
	v_mfma_f32_16x16x32_bf16 v[86:89], v[146:149], v[190:193], 0
	v_mfma_f32_16x16x32_bf16 v[86:89], v[162:165], v[204:207], v[86:89]
	v_mfma_f32_16x16x32_bf16 v[82:85], v[170:173], v[204:207], 0
	v_mfma_f32_16x16x32_bf16 v[82:85], v[166:169], v[190:193], v[82:85]
	v_mfma_f32_16x16x32_bf16 v[66:69], v[166:169], v[208:211], 0
	v_mfma_f32_16x16x32_bf16 v[66:69], v[170:173], v[212:215], v[66:69]
	v_mfma_f32_16x16x32_bf16 v[70:73], v[162:165], v[212:215], 0
	v_mfma_f32_16x16x32_bf16 v[70:73], v[146:149], v[208:211], v[70:73]
	s_setprio 0
	s_barrier
	ds_read_b128 v[174:177], v225 offset:16384
	ds_read_b128 v[178:181], v225 offset:17408
	ds_read_b128 v[182:185], v225 offset:18432
	ds_read_b128 v[186:189], v225 offset:19456
	ds_read_b128 v[190:193], v225 offset:20480
	ds_read_b128 v[204:207], v225 offset:21504
	ds_read_b128 v[208:211], v225 offset:22528
	ds_read_b128 v[212:215], v225 offset:23552
	s_add_i32 s0, s58, s15
	s_mov_b32 m0, s0
	s_nop 0
	global_load_lds_dwordx4 v152, s[30:31]
	s_add_i32 m0, s0, 0x2000
	s_add_u32 s0, s30, 0x80000
	s_addc_u32 s1, s31, 0
	s_add_i32 s58, s59, s15
	global_load_lds_dwordx4 v156, s[30:31]
	s_mov_b32 m0, s58
	s_nop 0
	global_load_lds_dwordx4 v152, s[0:1]
	s_add_i32 m0, s58, 0x2000
	s_nop 0
	global_load_lds_dwordx4 v156, s[0:1]
	s_waitcnt vmcnt(6)
	s_waitcnt lgkmcnt(0)
	v_mfma_f32_16x16x32_bf16 v[62:65], v[130:133], v[174:177], 0
	v_mfma_f32_16x16x32_bf16 v[62:65], v[134:137], v[178:181], v[62:65]
	s_barrier
	s_setprio 1
	v_mfma_f32_16x16x32_bf16 v[58:61], v[142:145], v[178:181], 0
	v_mfma_f32_16x16x32_bf16 v[58:61], v[138:141], v[174:177], v[58:61]
	v_mfma_f32_16x16x32_bf16 v[42:45], v[138:141], v[182:185], 0
	v_mfma_f32_16x16x32_bf16 v[42:45], v[142:145], v[186:189], v[42:45]
	v_mfma_f32_16x16x32_bf16 v[46:49], v[134:137], v[186:189], 0
	v_mfma_f32_16x16x32_bf16 v[46:49], v[130:133], v[182:185], v[46:49]
	v_mfma_f32_16x16x32_bf16 v[30:33], v[130:133], v[190:193], 0
	v_mfma_f32_16x16x32_bf16 v[30:33], v[134:137], v[204:207], v[30:33]
	v_mfma_f32_16x16x32_bf16 v[26:29], v[142:145], v[204:207], 0
	v_mfma_f32_16x16x32_bf16 v[26:29], v[138:141], v[190:193], v[26:29]
	v_mfma_f32_16x16x32_bf16 v[10:13], v[138:141], v[208:211], 0
	v_mfma_f32_16x16x32_bf16 v[10:13], v[142:145], v[212:215], v[10:13]
	v_mfma_f32_16x16x32_bf16 v[14:17], v[134:137], v[212:215], 0
	v_mfma_f32_16x16x32_bf16 v[14:17], v[130:133], v[208:211], v[14:17]
	v_mfma_f32_16x16x32_bf16 v[54:57], v[146:149], v[174:177], 0
	v_mfma_f32_16x16x32_bf16 v[54:57], v[162:165], v[178:181], v[54:57]
	v_mfma_f32_16x16x32_bf16 v[50:53], v[170:173], v[178:181], 0
	v_mfma_f32_16x16x32_bf16 v[50:53], v[166:169], v[174:177], v[50:53]
	v_mfma_f32_16x16x32_bf16 v[34:37], v[166:169], v[182:185], 0
	v_mfma_f32_16x16x32_bf16 v[34:37], v[170:173], v[186:189], v[34:37]
	v_mfma_f32_16x16x32_bf16 v[38:41], v[162:165], v[186:189], 0
	v_mfma_f32_16x16x32_bf16 v[38:41], v[146:149], v[182:185], v[38:41]
	v_mfma_f32_16x16x32_bf16 v[22:25], v[146:149], v[190:193], 0
	v_mfma_f32_16x16x32_bf16 v[22:25], v[162:165], v[204:207], v[22:25]
	v_mfma_f32_16x16x32_bf16 v[18:21], v[170:173], v[204:207], 0
	v_mfma_f32_16x16x32_bf16 v[18:21], v[166:169], v[190:193], v[18:21]
	v_mfma_f32_16x16x32_bf16 v[2:5], v[166:169], v[208:211], 0
	v_mfma_f32_16x16x32_bf16 v[2:5], v[170:173], v[212:215], v[2:5]
	v_mfma_f32_16x16x32_bf16 v[6:9], v[162:165], v[212:215], 0
	v_mfma_f32_16x16x32_bf16 v[6:9], v[146:149], v[208:211], v[6:9]
	s_setprio 0
	s_barrier
	s_mov_b32 m0, s38
	s_nop 0
	global_load_lds_dwordx4 v150, s[34:35]
	s_mov_b32 m0, s39
	s_nop 0
	global_load_lds_dwordx4 v154, s[34:35]
	ds_read_b128 v[130:133], v224 offset:32768
	ds_read_b128 v[134:137], v224 offset:33792
	ds_read_b128 v[138:141], v224 offset:34816
	ds_read_b128 v[142:145], v224 offset:35840
	ds_read_b128 v[146:149], v224 offset:49152
	ds_read_b128 v[162:165], v224 offset:50176
	ds_read_b128 v[166:169], v224 offset:51200
	ds_read_b128 v[170:173], v224 offset:52224
	ds_read_b128 v[174:177], v225 offset:32768
	ds_read_b128 v[178:181], v225 offset:33792
	ds_read_b128 v[182:185], v225 offset:34816
	ds_read_b128 v[186:189], v225 offset:35840
	ds_read_b128 v[190:193], v225 offset:36864
	ds_read_b128 v[204:207], v225 offset:37888
	ds_read_b128 v[208:211], v225 offset:38912
	ds_read_b128 v[212:215], v225 offset:39936
	s_add_i32 s58, 0, 0x18000
	s_add_i32 s59, 0, 0x1c000
	s_add_u32 s0, s34, 0x4000
	s_addc_u32 s1, s35, 0
	s_mov_b32 m0, s40
	s_nop 0
	global_load_lds_dwordx4 v150, s[0:1]
	s_mov_b32 m0, s41
	s_nop 0
	global_load_lds_dwordx4 v154, s[0:1]
	s_waitcnt vmcnt(8)
	s_waitcnt lgkmcnt(0)
	v_mfma_f32_16x16x32_bf16 v[126:129], v[130:133], v[174:177], v[126:129]
	v_mfma_f32_16x16x32_bf16 v[126:129], v[134:137], v[178:181], v[126:129]
	s_barrier
	s_setprio 1
	v_mfma_f32_16x16x32_bf16 v[122:125], v[142:145], v[178:181], v[122:125]
	v_mfma_f32_16x16x32_bf16 v[122:125], v[138:141], v[174:177], v[122:125]
	v_mfma_f32_16x16x32_bf16 v[106:109], v[138:141], v[182:185], v[106:109]
	v_mfma_f32_16x16x32_bf16 v[106:109], v[142:145], v[186:189], v[106:109]
	v_mfma_f32_16x16x32_bf16 v[110:113], v[134:137], v[186:189], v[110:113]
	v_mfma_f32_16x16x32_bf16 v[110:113], v[130:133], v[182:185], v[110:113]
	v_mfma_f32_16x16x32_bf16 v[94:97], v[130:133], v[190:193], v[94:97]
	v_mfma_f32_16x16x32_bf16 v[94:97], v[134:137], v[204:207], v[94:97]
	v_mfma_f32_16x16x32_bf16 v[90:93], v[142:145], v[204:207], v[90:93]
	v_mfma_f32_16x16x32_bf16 v[90:93], v[138:141], v[190:193], v[90:93]
	v_mfma_f32_16x16x32_bf16 v[74:77], v[138:141], v[208:211], v[74:77]
	v_mfma_f32_16x16x32_bf16 v[74:77], v[142:145], v[212:215], v[74:77]
	v_mfma_f32_16x16x32_bf16 v[78:81], v[134:137], v[212:215], v[78:81]
	v_mfma_f32_16x16x32_bf16 v[78:81], v[130:133], v[208:211], v[78:81]
	v_mfma_f32_16x16x32_bf16 v[118:121], v[146:149], v[174:177], v[118:121]
	v_mfma_f32_16x16x32_bf16 v[118:121], v[162:165], v[178:181], v[118:121]
	v_mfma_f32_16x16x32_bf16 v[114:117], v[170:173], v[178:181], v[114:117]
	v_mfma_f32_16x16x32_bf16 v[114:117], v[166:169], v[174:177], v[114:117]
	v_mfma_f32_16x16x32_bf16 v[98:101], v[166:169], v[182:185], v[98:101]
	v_mfma_f32_16x16x32_bf16 v[98:101], v[170:173], v[186:189], v[98:101]
	v_mfma_f32_16x16x32_bf16 v[102:105], v[162:165], v[186:189], v[102:105]
	v_mfma_f32_16x16x32_bf16 v[102:105], v[146:149], v[182:185], v[102:105]
	v_mfma_f32_16x16x32_bf16 v[86:89], v[146:149], v[190:193], v[86:89]
	v_mfma_f32_16x16x32_bf16 v[86:89], v[162:165], v[204:207], v[86:89]
	v_mfma_f32_16x16x32_bf16 v[82:85], v[170:173], v[204:207], v[82:85]
	v_mfma_f32_16x16x32_bf16 v[82:85], v[166:169], v[190:193], v[82:85]
	v_mfma_f32_16x16x32_bf16 v[66:69], v[166:169], v[208:211], v[66:69]
	v_mfma_f32_16x16x32_bf16 v[66:69], v[170:173], v[212:215], v[66:69]
	v_mfma_f32_16x16x32_bf16 v[70:73], v[162:165], v[212:215], v[70:73]
	v_mfma_f32_16x16x32_bf16 v[70:73], v[146:149], v[208:211], v[70:73]
	s_setprio 0
	s_barrier
	ds_read_b128 v[174:177], v225 offset:49152
	ds_read_b128 v[178:181], v225 offset:50176
	ds_read_b128 v[182:185], v225 offset:51200
	ds_read_b128 v[186:189], v225 offset:52224
	ds_read_b128 v[190:193], v225 offset:53248
	ds_read_b128 v[204:207], v225 offset:54272
	ds_read_b128 v[208:211], v225 offset:55296
	ds_read_b128 v[212:215], v225 offset:56320
	s_add_i32 s0, s58, s15
	s_add_u32 vcc_lo, s30, s94
	s_addc_u32 vcc_hi, s31, s95
	s_mov_b32 m0, s0
	s_nop 0
	global_load_lds_dwordx4 v152, vcc
	s_add_i32 m0, s0, 0x2000
	s_add_u32 s0, s30, 0x80080
	s_addc_u32 s1, s31, 0
	s_add_i32 s30, s59, s15
	global_load_lds_dwordx4 v156, vcc
	s_mov_b32 m0, s30
	s_nop 0
	global_load_lds_dwordx4 v152, s[0:1]
	s_add_i32 m0, s30, 0x2000
	s_nop 0
	global_load_lds_dwordx4 v156, s[0:1]
	s_waitcnt vmcnt(6)
	s_waitcnt lgkmcnt(0)
	v_mfma_f32_16x16x32_bf16 v[62:65], v[130:133], v[174:177], v[62:65]
	v_mfma_f32_16x16x32_bf16 v[62:65], v[134:137], v[178:181], v[62:65]
	s_barrier
	s_setprio 1
	v_mfma_f32_16x16x32_bf16 v[58:61], v[142:145], v[178:181], v[58:61]
	v_mfma_f32_16x16x32_bf16 v[58:61], v[138:141], v[174:177], v[58:61]
	v_mfma_f32_16x16x32_bf16 v[42:45], v[138:141], v[182:185], v[42:45]
	v_mfma_f32_16x16x32_bf16 v[42:45], v[142:145], v[186:189], v[42:45]
	v_mfma_f32_16x16x32_bf16 v[46:49], v[134:137], v[186:189], v[46:49]
	v_mfma_f32_16x16x32_bf16 v[46:49], v[130:133], v[182:185], v[46:49]
	v_mfma_f32_16x16x32_bf16 v[30:33], v[130:133], v[190:193], v[30:33]
	v_mfma_f32_16x16x32_bf16 v[30:33], v[134:137], v[204:207], v[30:33]
	v_mfma_f32_16x16x32_bf16 v[26:29], v[142:145], v[204:207], v[26:29]
	v_mfma_f32_16x16x32_bf16 v[26:29], v[138:141], v[190:193], v[26:29]
	v_mfma_f32_16x16x32_bf16 v[10:13], v[138:141], v[208:211], v[10:13]
	v_mfma_f32_16x16x32_bf16 v[10:13], v[142:145], v[212:215], v[10:13]
	s_add_i32 s57, s57, 2
	v_mfma_f32_16x16x32_bf16 v[14:17], v[134:137], v[212:215], v[14:17]
	v_mfma_f32_16x16x32_bf16 v[14:17], v[130:133], v[208:211], v[14:17]
	s_add_u32 s50, s50, 0x100
	v_mfma_f32_16x16x32_bf16 v[54:57], v[146:149], v[174:177], v[54:57]
	v_mfma_f32_16x16x32_bf16 v[54:57], v[162:165], v[178:181], v[54:57]
	s_addc_u32 s51, s51, 0
	v_mfma_f32_16x16x32_bf16 v[50:53], v[170:173], v[178:181], v[50:53]
	v_mfma_f32_16x16x32_bf16 v[50:53], v[166:169], v[174:177], v[50:53]
	s_cmp_gt_u32 s57, 29
	v_mfma_f32_16x16x32_bf16 v[34:37], v[166:169], v[182:185], v[34:37]
	v_mfma_f32_16x16x32_bf16 v[34:37], v[170:173], v[186:189], v[34:37]
	s_mov_b64 s[0:1], s[4:5]
	v_mfma_f32_16x16x32_bf16 v[38:41], v[162:165], v[186:189], v[38:41]
	v_mfma_f32_16x16x32_bf16 v[38:41], v[146:149], v[182:185], v[38:41]
	v_mfma_f32_16x16x32_bf16 v[22:25], v[146:149], v[190:193], v[22:25]
	v_mfma_f32_16x16x32_bf16 v[22:25], v[162:165], v[204:207], v[22:25]
	v_mfma_f32_16x16x32_bf16 v[18:21], v[170:173], v[204:207], v[18:21]
	v_mfma_f32_16x16x32_bf16 v[18:21], v[166:169], v[190:193], v[18:21]
	v_mfma_f32_16x16x32_bf16 v[2:5], v[166:169], v[208:211], v[2:5]
	v_mfma_f32_16x16x32_bf16 v[2:5], v[170:173], v[212:215], v[2:5]
	v_mfma_f32_16x16x32_bf16 v[6:9], v[162:165], v[212:215], v[6:9]
	v_mfma_f32_16x16x32_bf16 v[6:9], v[146:149], v[208:211], v[6:9]
	s_setprio 0
	s_barrier
	s_cbranch_scc1 .Lpeel_exit_0
	.p2align	6

.LBB0_303:
	s_ashr_i32 s25, s24, 31
	s_lshl_b64 s[28:29], s[24:25], 20
	v_readlane_b32 s25, v254, 62
	s_add_u32 s25, s25, s28
	v_readlane_b32 s27, v254, 63
	s_addc_u32 s27, s27, s29
	s_and_b64 s[28:29], s[4:5], exec
	s_cselect_b32 s29, s27, s39
	s_cselect_b32 s25, s25, s38
	s_ashr_i32 s27, s26, 31
	s_lshl_b64 s[40:41], s[26:27], 7
	s_add_u32 s28, s25, s40
	s_addc_u32 s29, s29, s41
	s_and_b64 s[70:71], s[4:5], exec
	s_cselect_b32 s27, s40, 0
	s_cselect_b32 s25, s41, 0
	s_add_u32 s30, s30, s27
	s_addc_u32 s31, s31, s25
	s_cmp_lt_i32 s35, 1
	s_cbranch_scc1 .LBB0_331
	s_and_b64 s[4:5], s[4:5], exec
	s_cselect_b32 s25, s29, s39
	s_cselect_b32 s27, s28, s38
	s_add_i32 s37, s35, -2
	s_add_u32 s51, s38, 0x100
	v_mov_b64_e32 v[8:9], v[4:5]
	v_mov_b64_e32 v[20:21], v[4:5]
	v_mov_b64_e32 v[24:25], v[4:5]
	v_mov_b64_e32 v[36:37], v[4:5]
	v_mov_b64_e32 v[40:41], v[4:5]
	v_mov_b64_e32 v[52:53], v[4:5]
	v_mov_b64_e32 v[56:57], v[4:5]
	v_mov_b64_e32 v[12:13], v[4:5]
	v_mov_b64_e32 v[16:17], v[4:5]
	v_mov_b64_e32 v[28:29], v[4:5]
	v_mov_b64_e32 v[32:33], v[4:5]
	v_mov_b64_e32 v[44:45], v[4:5]
	v_mov_b64_e32 v[48:49], v[4:5]
	v_mov_b64_e32 v[60:61], v[4:5]
	v_mov_b64_e32 v[64:65], v[4:5]
	v_mov_b64_e32 v[68:69], v[4:5]
	v_mov_b64_e32 v[72:73], v[4:5]
	v_mov_b64_e32 v[84:85], v[4:5]
	v_mov_b64_e32 v[88:89], v[4:5]
	v_mov_b64_e32 v[100:101], v[4:5]
	v_mov_b64_e32 v[104:105], v[4:5]
	v_mov_b64_e32 v[116:117], v[4:5]
	v_mov_b64_e32 v[120:121], v[4:5]
	v_mov_b64_e32 v[76:77], v[4:5]
	v_mov_b64_e32 v[80:81], v[4:5]
	v_mov_b64_e32 v[92:93], v[4:5]
	v_mov_b64_e32 v[96:97], v[4:5]
	v_mov_b64_e32 v[108:109], v[4:5]
	v_mov_b64_e32 v[112:113], v[4:5]
	v_mov_b64_e32 v[124:125], v[4:5]
	v_mov_b64_e32 v[128:129], v[4:5]
	s_addc_u32 s70, s39, 0
	s_mov_b32 s38, 0
	v_mov_b64_e32 v[6:7], v[2:3]
	v_mov_b64_e32 v[18:19], v[2:3]
	v_mov_b64_e32 v[22:23], v[2:3]
	v_mov_b64_e32 v[34:35], v[2:3]
	v_mov_b64_e32 v[38:39], v[2:3]
	v_mov_b64_e32 v[50:51], v[2:3]
	v_mov_b64_e32 v[54:55], v[2:3]
	v_mov_b64_e32 v[10:11], v[2:3]
	v_mov_b64_e32 v[14:15], v[2:3]
	v_mov_b64_e32 v[26:27], v[2:3]
	v_mov_b64_e32 v[30:31], v[2:3]
	v_mov_b64_e32 v[42:43], v[2:3]
	v_mov_b64_e32 v[46:47], v[2:3]
	v_mov_b64_e32 v[58:59], v[2:3]
	v_mov_b64_e32 v[62:63], v[2:3]
	v_mov_b64_e32 v[66:67], v[2:3]
	v_mov_b64_e32 v[70:71], v[2:3]
	v_mov_b64_e32 v[82:83], v[2:3]
	v_mov_b64_e32 v[86:87], v[2:3]
	v_mov_b64_e32 v[98:99], v[2:3]
	v_mov_b64_e32 v[102:103], v[2:3]
	v_mov_b64_e32 v[114:115], v[2:3]
	v_mov_b64_e32 v[118:119], v[2:3]
	v_mov_b64_e32 v[74:75], v[2:3]
	v_mov_b64_e32 v[78:79], v[2:3]
	v_mov_b64_e32 v[90:91], v[2:3]
	v_mov_b64_e32 v[94:95], v[2:3]
	v_mov_b64_e32 v[106:107], v[2:3]
	v_mov_b64_e32 v[110:111], v[2:3]
	v_mov_b64_e32 v[122:123], v[2:3]
	v_mov_b64_e32 v[126:127], v[2:3]
	.p2align	6

.LBB0_529:
	s_lshl_b32 s10, s30, 8
	s_ashr_i32 s11, s10, 31
	s_lshl_b64 s[10:11], s[10:11], 12
	s_add_u32 s10, s86, s10
	s_addc_u32 s11, s87, s11
	s_and_b64 s[12:13], s[2:3], exec
	s_cselect_b32 s34, s11, s15
	s_cselect_b32 s35, s10, s14
	s_ashr_i32 s9, s8, 31
	s_lshl_b64 s[12:13], s[8:9], 20
	v_readlane_b32 s9, v254, 62
	s_add_u32 s12, s9, s12
	v_readlane_b32 s9, v254, 63
	s_addc_u32 s13, s9, s13
	s_and_b64 s[18:19], s[2:3], exec
	s_cselect_b32 s9, s13, s17
	s_cselect_b32 s36, s12, s16
	s_add_u32 s14, s14, 0x80080
	s_addc_u32 s15, s15, 0
	s_add_u32 s37, s16, 0x100
	s_addc_u32 s38, s17, 0
	s_mov_b32 s39, -2
	s_add_u32 vcc_lo, s14, 0xfff80000
	s_addc_u32 vcc_hi, s15, -1
	s_mov_b32 m0, s27
	s_nop 0
	global_load_lds_dwordx4 v138, vcc
	s_mov_b32 m0, s28
	s_nop 0
	global_load_lds_dwordx4 v140, vcc
	ds_read_b128 v[152:155], v145
	ds_read_b128 v[156:159], v145 offset:1024
	ds_read_b128 v[160:163], v145 offset:2048
	ds_read_b128 v[164:167], v145 offset:3072
	ds_read_b128 v[168:171], v145 offset:16384
	ds_read_b128 v[172:175], v145 offset:17408
	ds_read_b128 v[176:179], v145 offset:18432
	ds_read_b128 v[180:183], v145 offset:19456
	ds_read_b128 v[184:187], v151
	ds_read_b128 v[188:191], v151 offset:1024
	ds_read_b128 v[204:207], v151 offset:2048
	ds_read_b128 v[208:211], v151 offset:3072
	ds_read_b128 v[212:215], v151 offset:4096
	ds_read_b128 v[216:219], v151 offset:5120
	ds_read_b128 v[220:223], v151 offset:6144
	ds_read_b128 v[224:227], v151 offset:7168
	s_add_u32 s16, s14, 0xfff80080
	s_addc_u32 s17, s15, -1
	s_add_i32 s40, 0, 0x10000
	s_cmp_eq_u32 s39, 28
	s_cselect_b32 s19, s34, s17
	s_cselect_b32 s18, s35, s16
	s_cselect_b32 s17, s9, s38
	s_cselect_b32 s16, s36, s37
	s_add_i32 s42, 0, 0x14000
	s_add_i32 m0, s23, 0xc000
	s_nop 0
	global_load_lds_dwordx4 v138, s[14:15]
	s_add_i32 m0, s23, 0xe000
	s_nop 0
	global_load_lds_dwordx4 v140, s[14:15]
	s_waitcnt vmcnt(20)
	s_waitcnt lgkmcnt(0)
	v_mfma_f32_16x16x32_bf16 v[126:129], v[152:155], v[184:187], 0
	v_mfma_f32_16x16x32_bf16 v[126:129], v[156:159], v[188:191], v[126:129]
	s_barrier
	s_setprio 1
	v_mfma_f32_16x16x32_bf16 v[122:125], v[164:167], v[188:191], 0
	v_mfma_f32_16x16x32_bf16 v[122:125], v[160:163], v[184:187], v[122:125]
	v_mfma_f32_16x16x32_bf16 v[106:109], v[160:163], v[204:207], 0
	v_mfma_f32_16x16x32_bf16 v[106:109], v[164:167], v[208:211], v[106:109]
	v_mfma_f32_16x16x32_bf16 v[110:113], v[156:159], v[208:211], 0
	v_mfma_f32_16x16x32_bf16 v[110:113], v[152:155], v[204:207], v[110:113]
	v_mfma_f32_16x16x32_bf16 v[94:97], v[152:155], v[212:215], 0
	v_mfma_f32_16x16x32_bf16 v[94:97], v[156:159], v[216:219], v[94:97]
	v_mfma_f32_16x16x32_bf16 v[90:93], v[164:167], v[216:219], 0
	v_mfma_f32_16x16x32_bf16 v[90:93], v[160:163], v[212:215], v[90:93]
	v_mfma_f32_16x16x32_bf16 v[74:77], v[160:163], v[220:223], 0
	v_mfma_f32_16x16x32_bf16 v[74:77], v[164:167], v[224:227], v[74:77]
	v_mfma_f32_16x16x32_bf16 v[78:81], v[156:159], v[224:227], 0
	v_mfma_f32_16x16x32_bf16 v[78:81], v[152:155], v[220:223], v[78:81]
	v_mfma_f32_16x16x32_bf16 v[118:121], v[168:171], v[184:187], 0
	v_mfma_f32_16x16x32_bf16 v[118:121], v[172:175], v[188:191], v[118:121]
	v_mfma_f32_16x16x32_bf16 v[114:117], v[180:183], v[188:191], 0
	v_mfma_f32_16x16x32_bf16 v[114:117], v[176:179], v[184:187], v[114:117]
	v_mfma_f32_16x16x32_bf16 v[98:101], v[176:179], v[204:207], 0
	v_mfma_f32_16x16x32_bf16 v[98:101], v[180:183], v[208:211], v[98:101]
	v_mfma_f32_16x16x32_bf16 v[102:105], v[172:175], v[208:211], 0
	v_mfma_f32_16x16x32_bf16 v[102:105], v[168:171], v[204:207], v[102:105]
	v_mfma_f32_16x16x32_bf16 v[86:89], v[168:171], v[212:215], 0
	v_mfma_f32_16x16x32_bf16 v[86:89], v[172:175], v[216:219], v[86:89]
	v_mfma_f32_16x16x32_bf16 v[82:85], v[180:183], v[216:219], 0
	v_mfma_f32_16x16x32_bf16 v[82:85], v[176:179], v[212:215], v[82:85]
	v_mfma_f32_16x16x32_bf16 v[66:69], v[176:179], v[220:223], 0
	v_mfma_f32_16x16x32_bf16 v[66:69], v[180:183], v[224:227], v[66:69]
	v_mfma_f32_16x16x32_bf16 v[70:73], v[172:175], v[224:227], 0
	v_mfma_f32_16x16x32_bf16 v[70:73], v[168:171], v[220:223], v[70:73]
	s_setprio 0
	s_barrier
	ds_read_b128 v[184:187], v151 offset:16384
	ds_read_b128 v[188:191], v151 offset:17408
	ds_read_b128 v[204:207], v151 offset:18432
	ds_read_b128 v[208:211], v151 offset:19456
	ds_read_b128 v[212:215], v151 offset:20480
	ds_read_b128 v[216:219], v151 offset:21504
	ds_read_b128 v[220:223], v151 offset:22528
	ds_read_b128 v[224:227], v151 offset:23552
	s_add_i32 s40, s40, s22
	s_mov_b32 m0, s40
	s_nop 0
	global_load_lds_dwordx4 v134, s[16:17]
	s_add_i32 m0, s40, 0x2000
	s_add_u32 s40, s16, 0x80000
	s_addc_u32 s41, s17, 0
	s_add_i32 s42, s42, s22
	global_load_lds_dwordx4 v130, s[16:17]
	s_mov_b32 m0, s42
	s_nop 0
	global_load_lds_dwordx4 v134, s[40:41]
	s_add_i32 m0, s42, 0x2000
	s_nop 0
	global_load_lds_dwordx4 v130, s[40:41]
	s_waitcnt vmcnt(6)
	s_waitcnt lgkmcnt(0)
	v_mfma_f32_16x16x32_bf16 v[62:65], v[152:155], v[184:187], 0
	v_mfma_f32_16x16x32_bf16 v[62:65], v[156:159], v[188:191], v[62:65]
	s_barrier
	s_setprio 1
	v_mfma_f32_16x16x32_bf16 v[58:61], v[164:167], v[188:191], 0
	v_mfma_f32_16x16x32_bf16 v[58:61], v[160:163], v[184:187], v[58:61]
	v_mfma_f32_16x16x32_bf16 v[42:45], v[160:163], v[204:207], 0
	v_mfma_f32_16x16x32_bf16 v[42:45], v[164:167], v[208:211], v[42:45]
	v_mfma_f32_16x16x32_bf16 v[46:49], v[156:159], v[208:211], 0
	v_mfma_f32_16x16x32_bf16 v[46:49], v[152:155], v[204:207], v[46:49]
	v_mfma_f32_16x16x32_bf16 v[30:33], v[152:155], v[212:215], 0
	v_mfma_f32_16x16x32_bf16 v[30:33], v[156:159], v[216:219], v[30:33]
	v_mfma_f32_16x16x32_bf16 v[26:29], v[164:167], v[216:219], 0
	v_mfma_f32_16x16x32_bf16 v[26:29], v[160:163], v[212:215], v[26:29]
	v_mfma_f32_16x16x32_bf16 v[10:13], v[160:163], v[220:223], 0
	v_mfma_f32_16x16x32_bf16 v[10:13], v[164:167], v[224:227], v[10:13]
	v_mfma_f32_16x16x32_bf16 v[14:17], v[156:159], v[224:227], 0
	v_mfma_f32_16x16x32_bf16 v[14:17], v[152:155], v[220:223], v[14:17]
	v_mfma_f32_16x16x32_bf16 v[54:57], v[168:171], v[184:187], 0
	v_mfma_f32_16x16x32_bf16 v[54:57], v[172:175], v[188:191], v[54:57]
	v_mfma_f32_16x16x32_bf16 v[50:53], v[180:183], v[188:191], 0
	v_mfma_f32_16x16x32_bf16 v[50:53], v[176:179], v[184:187], v[50:53]
	v_mfma_f32_16x16x32_bf16 v[34:37], v[176:179], v[204:207], 0
	v_mfma_f32_16x16x32_bf16 v[34:37], v[180:183], v[208:211], v[34:37]
	v_mfma_f32_16x16x32_bf16 v[38:41], v[172:175], v[208:211], 0
	v_mfma_f32_16x16x32_bf16 v[38:41], v[168:171], v[204:207], v[38:41]
	v_mfma_f32_16x16x32_bf16 v[22:25], v[168:171], v[212:215], 0
	v_mfma_f32_16x16x32_bf16 v[22:25], v[172:175], v[216:219], v[22:25]
	v_mfma_f32_16x16x32_bf16 v[18:21], v[180:183], v[216:219], 0
	v_mfma_f32_16x16x32_bf16 v[18:21], v[176:179], v[212:215], v[18:21]
	v_mfma_f32_16x16x32_bf16 v[2:5], v[176:179], v[220:223], 0
	v_mfma_f32_16x16x32_bf16 v[2:5], v[180:183], v[224:227], v[2:5]
	v_mfma_f32_16x16x32_bf16 v[6:9], v[172:175], v[224:227], 0
	v_mfma_f32_16x16x32_bf16 v[6:9], v[168:171], v[220:223], v[6:9]
	s_setprio 0
	s_barrier
	s_mov_b32 m0, s23
	s_nop 0
	global_load_lds_dwordx4 v136, s[18:19]
	s_mov_b32 m0, s24
	s_nop 0
	global_load_lds_dwordx4 v132, s[18:19]
	ds_read_b128 v[152:155], v145 offset:32768
	ds_read_b128 v[156:159], v145 offset:33792
	ds_read_b128 v[160:163], v145 offset:34816
	ds_read_b128 v[164:167], v145 offset:35840
	ds_read_b128 v[168:171], v145 offset:49152
	ds_read_b128 v[172:175], v145 offset:50176
	ds_read_b128 v[176:179], v145 offset:51200
	ds_read_b128 v[180:183], v145 offset:52224
	ds_read_b128 v[184:187], v151 offset:32768
	ds_read_b128 v[188:191], v151 offset:33792
	ds_read_b128 v[204:207], v151 offset:34816
	ds_read_b128 v[208:211], v151 offset:35840
	ds_read_b128 v[212:215], v151 offset:36864
	ds_read_b128 v[216:219], v151 offset:37888
	ds_read_b128 v[220:223], v151 offset:38912
	ds_read_b128 v[224:227], v151 offset:39936
	s_add_i32 s40, 0, 0x18000
	s_add_i32 s41, 0, 0x1c000
	s_add_u32 s18, s18, 0x80000
	s_addc_u32 s19, s19, 0
	s_mov_b32 m0, s25
	s_nop 0
	global_load_lds_dwordx4 v136, s[18:19]
	s_mov_b32 m0, s26
	s_nop 0
	global_load_lds_dwordx4 v132, s[18:19]
	s_waitcnt vmcnt(8)
	s_waitcnt lgkmcnt(0)
	v_mfma_f32_16x16x32_bf16 v[126:129], v[152:155], v[184:187], v[126:129]
	v_mfma_f32_16x16x32_bf16 v[126:129], v[156:159], v[188:191], v[126:129]
	s_barrier
	s_setprio 1
	v_mfma_f32_16x16x32_bf16 v[122:125], v[164:167], v[188:191], v[122:125]
	v_mfma_f32_16x16x32_bf16 v[122:125], v[160:163], v[184:187], v[122:125]
	v_mfma_f32_16x16x32_bf16 v[106:109], v[160:163], v[204:207], v[106:109]
	v_mfma_f32_16x16x32_bf16 v[106:109], v[164:167], v[208:211], v[106:109]
	v_mfma_f32_16x16x32_bf16 v[110:113], v[156:159], v[208:211], v[110:113]
	v_mfma_f32_16x16x32_bf16 v[110:113], v[152:155], v[204:207], v[110:113]
	v_mfma_f32_16x16x32_bf16 v[94:97], v[152:155], v[212:215], v[94:97]
	v_mfma_f32_16x16x32_bf16 v[94:97], v[156:159], v[216:219], v[94:97]
	v_mfma_f32_16x16x32_bf16 v[90:93], v[164:167], v[216:219], v[90:93]
	v_mfma_f32_16x16x32_bf16 v[90:93], v[160:163], v[212:215], v[90:93]
	v_mfma_f32_16x16x32_bf16 v[74:77], v[160:163], v[220:223], v[74:77]
	v_mfma_f32_16x16x32_bf16 v[74:77], v[164:167], v[224:227], v[74:77]
	v_mfma_f32_16x16x32_bf16 v[78:81], v[156:159], v[224:227], v[78:81]
	v_mfma_f32_16x16x32_bf16 v[78:81], v[152:155], v[220:223], v[78:81]
	v_mfma_f32_16x16x32_bf16 v[118:121], v[168:171], v[184:187], v[118:121]
	v_mfma_f32_16x16x32_bf16 v[118:121], v[172:175], v[188:191], v[118:121]
	v_mfma_f32_16x16x32_bf16 v[114:117], v[180:183], v[188:191], v[114:117]
	v_mfma_f32_16x16x32_bf16 v[114:117], v[176:179], v[184:187], v[114:117]
	v_mfma_f32_16x16x32_bf16 v[98:101], v[176:179], v[204:207], v[98:101]
	v_mfma_f32_16x16x32_bf16 v[98:101], v[180:183], v[208:211], v[98:101]
	v_mfma_f32_16x16x32_bf16 v[102:105], v[172:175], v[208:211], v[102:105]
	v_mfma_f32_16x16x32_bf16 v[102:105], v[168:171], v[204:207], v[102:105]
	v_mfma_f32_16x16x32_bf16 v[86:89], v[168:171], v[212:215], v[86:89]
	v_mfma_f32_16x16x32_bf16 v[86:89], v[172:175], v[216:219], v[86:89]
	v_mfma_f32_16x16x32_bf16 v[82:85], v[180:183], v[216:219], v[82:85]
	v_mfma_f32_16x16x32_bf16 v[82:85], v[176:179], v[212:215], v[82:85]
	v_mfma_f32_16x16x32_bf16 v[66:69], v[176:179], v[220:223], v[66:69]
	v_mfma_f32_16x16x32_bf16 v[66:69], v[180:183], v[224:227], v[66:69]
	v_mfma_f32_16x16x32_bf16 v[70:73], v[172:175], v[224:227], v[70:73]
	v_mfma_f32_16x16x32_bf16 v[70:73], v[168:171], v[220:223], v[70:73]
	s_setprio 0
	s_barrier
	ds_read_b128 v[184:187], v151 offset:49152
	ds_read_b128 v[188:191], v151 offset:50176
	ds_read_b128 v[204:207], v151 offset:51200
	ds_read_b128 v[208:211], v151 offset:52224
	ds_read_b128 v[212:215], v151 offset:53248
	ds_read_b128 v[216:219], v151 offset:54272
	ds_read_b128 v[220:223], v151 offset:55296
	ds_read_b128 v[224:227], v151 offset:56320
	s_add_i32 s18, s40, s22
	s_add_u32 vcc_lo, s16, s94
	s_addc_u32 vcc_hi, s17, s95
	s_mov_b32 m0, s18
	s_nop 0
	global_load_lds_dwordx4 v134, vcc
	s_add_i32 m0, s18, 0x2000
	s_add_u32 s16, s16, 0x80080
	s_addc_u32 s17, s17, 0
	s_add_i32 s18, s41, s22
	global_load_lds_dwordx4 v130, vcc
	s_mov_b32 m0, s18
	s_nop 0
	global_load_lds_dwordx4 v134, s[16:17]
	s_add_i32 m0, s18, 0x2000
	s_nop 0
	global_load_lds_dwordx4 v130, s[16:17]
	s_waitcnt vmcnt(6)
	s_waitcnt lgkmcnt(0)
	v_mfma_f32_16x16x32_bf16 v[62:65], v[152:155], v[184:187], v[62:65]
	v_mfma_f32_16x16x32_bf16 v[62:65], v[156:159], v[188:191], v[62:65]
	s_barrier
	s_setprio 1
	v_mfma_f32_16x16x32_bf16 v[58:61], v[164:167], v[188:191], v[58:61]
	v_mfma_f32_16x16x32_bf16 v[58:61], v[160:163], v[184:187], v[58:61]
	v_mfma_f32_16x16x32_bf16 v[42:45], v[160:163], v[204:207], v[42:45]
	v_mfma_f32_16x16x32_bf16 v[42:45], v[164:167], v[208:211], v[42:45]
	v_mfma_f32_16x16x32_bf16 v[46:49], v[156:159], v[208:211], v[46:49]
	v_mfma_f32_16x16x32_bf16 v[46:49], v[152:155], v[204:207], v[46:49]
	v_mfma_f32_16x16x32_bf16 v[30:33], v[152:155], v[212:215], v[30:33]
	v_mfma_f32_16x16x32_bf16 v[30:33], v[156:159], v[216:219], v[30:33]
	v_mfma_f32_16x16x32_bf16 v[26:29], v[164:167], v[216:219], v[26:29]
	v_mfma_f32_16x16x32_bf16 v[26:29], v[160:163], v[212:215], v[26:29]
	v_mfma_f32_16x16x32_bf16 v[10:13], v[160:163], v[220:223], v[10:13]
	v_mfma_f32_16x16x32_bf16 v[10:13], v[164:167], v[224:227], v[10:13]
	s_add_i32 s39, s39, 2
	v_mfma_f32_16x16x32_bf16 v[14:17], v[156:159], v[224:227], v[14:17]
	v_mfma_f32_16x16x32_bf16 v[14:17], v[152:155], v[220:223], v[14:17]
	s_add_u32 s14, s14, 0x100
	v_mfma_f32_16x16x32_bf16 v[54:57], v[168:171], v[184:187], v[54:57]
	v_mfma_f32_16x16x32_bf16 v[54:57], v[172:175], v[188:191], v[54:57]
	s_addc_u32 s15, s15, 0
	v_mfma_f32_16x16x32_bf16 v[50:53], v[180:183], v[188:191], v[50:53]
	v_mfma_f32_16x16x32_bf16 v[50:53], v[176:179], v[184:187], v[50:53]
	s_add_u32 s37, s37, 0x100
	v_mfma_f32_16x16x32_bf16 v[34:37], v[176:179], v[204:207], v[34:37]
	v_mfma_f32_16x16x32_bf16 v[34:37], v[180:183], v[208:211], v[34:37]
	s_addc_u32 s38, s38, 0
	v_mfma_f32_16x16x32_bf16 v[38:41], v[172:175], v[208:211], v[38:41]
	v_mfma_f32_16x16x32_bf16 v[38:41], v[168:171], v[204:207], v[38:41]
	s_cmp_gt_u32 s39, 29
	v_mfma_f32_16x16x32_bf16 v[22:25], v[168:171], v[212:215], v[22:25]
	v_mfma_f32_16x16x32_bf16 v[22:25], v[172:175], v[216:219], v[22:25]
	v_mfma_f32_16x16x32_bf16 v[18:21], v[180:183], v[216:219], v[18:21]
	v_mfma_f32_16x16x32_bf16 v[18:21], v[176:179], v[212:215], v[18:21]
	v_mfma_f32_16x16x32_bf16 v[2:5], v[176:179], v[220:223], v[2:5]
	v_mfma_f32_16x16x32_bf16 v[2:5], v[180:183], v[224:227], v[2:5]
	v_mfma_f32_16x16x32_bf16 v[6:9], v[172:175], v[224:227], v[6:9]
	v_mfma_f32_16x16x32_bf16 v[6:9], v[168:171], v[220:223], v[6:9]
	s_setprio 0
	s_barrier
	s_cbranch_scc1 .Lpeel_exit_2
	.p2align	6

.LBB0_768:
	s_add_i32 s56, s56, 2
	s_add_u32 s22, s22, 0x100
	s_addc_u32 s23, s23, 0
	s_add_u32 s54, s54, 0x100
	v_add_u32_e32 v130, 1, v130
	s_addc_u32 s55, s55, 0
	s_and_b64 vcc, exec, s[24:25]
	s_cbranch_vccnz .LBB0_771
	.p2align	6

.LBB0_797:
	s_movk_i32 s68, 0x6000
	s_mov_b32 s69, 0x20000
	s_mov_b32 s73, 0x26000
	s_mov_b32 s76, 0x14000
	s_mov_b32 s77, 0x16000
	s_add_i32 s84, s84, 2
	s_and_b64 vcc, exec, s[38:39]
	s_cbranch_vccnz .LBB0_801
	.p2align	6

.LBB0_849:
	s_add_u32 s18, s18, 0x80
	s_addc_u32 s19, s19, 0
	s_add_u32 s51, s20, 0x100
	s_waitcnt lgkmcnt(0)
	s_waitcnt vmcnt(0)
	s_addc_u32 s54, s21, 0
	s_mov_b32 s20, 0
	s_sub_u32 vcc_lo, s18, s12
	s_subb_u32 vcc_hi, s19, 0
	s_mov_b32 m0, s33
	s_nop 0
	global_load_lds_dwordx4 v210, vcc
	s_mov_b32 m0, s34
	s_nop 0
	global_load_lds_dwordx4 v212, vcc
	ds_read_b128 v[66:69], v198
	ds_read_b128 v[78:81], v198 offset:1024
	ds_read_b128 v[82:85], v198 offset:2048
	ds_read_b128 v[98:101], v198 offset:3072
	ds_read_b128 v[106:109], v198 offset:16384
	ds_read_b128 v[118:121], v198 offset:17408
	ds_read_b128 v[130:133], v198 offset:18432
	ds_read_b128 v[142:145], v198 offset:19456
	ds_read_b128 v[150:153], v234
	ds_read_b128 v[154:157], v234 offset:1024
	ds_read_b128 v[158:161], v234 offset:2048
	ds_read_b128 v[162:165], v234 offset:3072
	ds_read_b128 v[170:173], v234 offset:4096
	ds_read_b128 v[174:177], v234 offset:5120
	ds_read_b128 v[178:181], v234 offset:6144
	ds_read_b128 v[190:193], v234 offset:7168
	s_add_i32 s55, s20, 2
	s_add_u32 s56, s18, 0x80
	s_addc_u32 s21, s19, 0
	s_add_i32 s58, 0, 0x10000
	s_cmp_eq_u32 s35, s20
	s_cselect_b32 s21, s1, s21
	s_cselect_b32 s20, s0, s56
	s_cselect_b32 s57, s17, s54
	s_cselect_b32 s56, s16, s51
	s_add_i32 s59, 0, 0x14000
	s_add_i32 m0, s26, 0xc000
	s_nop 0
	global_load_lds_dwordx4 v210, s[18:19]
	s_add_i32 m0, s26, 0xe000
	s_nop 0
	global_load_lds_dwordx4 v212, s[18:19]
	s_waitcnt vmcnt(28)
	s_waitcnt lgkmcnt(0)
	v_mfma_f32_16x16x32_bf16 v[186:189], v[66:69], v[150:153], 0
	v_mfma_f32_16x16x32_bf16 v[186:189], v[78:81], v[154:157], v[186:189]
	s_barrier
	s_setprio 1
	v_mfma_f32_16x16x32_bf16 v[182:185], v[98:101], v[154:157], 0
	v_mfma_f32_16x16x32_bf16 v[182:185], v[82:85], v[150:153], v[182:185]
	v_mfma_f32_16x16x32_bf16 v[134:137], v[82:85], v[158:161], 0
	v_mfma_f32_16x16x32_bf16 v[134:137], v[98:101], v[162:165], v[134:137]
	v_mfma_f32_16x16x32_bf16 v[138:141], v[78:81], v[162:165], 0
	v_mfma_f32_16x16x32_bf16 v[138:141], v[66:69], v[158:161], v[138:141]
	v_mfma_f32_16x16x32_bf16 v[114:117], v[66:69], v[170:173], 0
	v_mfma_f32_16x16x32_bf16 v[114:117], v[78:81], v[174:177], v[114:117]
	v_mfma_f32_16x16x32_bf16 v[110:113], v[98:101], v[174:177], 0
	v_mfma_f32_16x16x32_bf16 v[110:113], v[82:85], v[170:173], v[110:113]
	v_mfma_f32_16x16x32_bf16 v[86:89], v[82:85], v[178:181], 0
	v_mfma_f32_16x16x32_bf16 v[86:89], v[98:101], v[190:193], v[86:89]
	v_mfma_f32_16x16x32_bf16 v[90:93], v[78:81], v[190:193], 0
	v_mfma_f32_16x16x32_bf16 v[90:93], v[66:69], v[178:181], v[90:93]
	v_mfma_f32_16x16x32_bf16 v[166:169], v[106:109], v[150:153], 0
	v_mfma_f32_16x16x32_bf16 v[166:169], v[118:121], v[154:157], v[166:169]
	v_mfma_f32_16x16x32_bf16 v[146:149], v[142:145], v[154:157], 0
	v_mfma_f32_16x16x32_bf16 v[146:149], v[130:133], v[150:153], v[146:149]
	v_mfma_f32_16x16x32_bf16 v[122:125], v[130:133], v[158:161], 0
	v_mfma_f32_16x16x32_bf16 v[122:125], v[142:145], v[162:165], v[122:125]
	v_mfma_f32_16x16x32_bf16 v[126:129], v[118:121], v[162:165], 0
	v_mfma_f32_16x16x32_bf16 v[126:129], v[106:109], v[158:161], v[126:129]
	v_mfma_f32_16x16x32_bf16 v[102:105], v[106:109], v[170:173], 0
	v_mfma_f32_16x16x32_bf16 v[102:105], v[118:121], v[174:177], v[102:105]
	v_mfma_f32_16x16x32_bf16 v[94:97], v[142:145], v[174:177], 0
	v_mfma_f32_16x16x32_bf16 v[94:97], v[130:133], v[170:173], v[94:97]
	v_mfma_f32_16x16x32_bf16 v[70:73], v[130:133], v[178:181], 0
	v_mfma_f32_16x16x32_bf16 v[70:73], v[142:145], v[190:193], v[70:73]
	v_mfma_f32_16x16x32_bf16 v[74:77], v[118:121], v[190:193], 0
	v_mfma_f32_16x16x32_bf16 v[74:77], v[106:109], v[178:181], v[74:77]
	s_setprio 0
	s_barrier
	ds_read_b128 v[150:153], v234 offset:16384
	ds_read_b128 v[154:157], v234 offset:17408
	ds_read_b128 v[158:161], v234 offset:18432
	ds_read_b128 v[162:165], v234 offset:19456
	ds_read_b128 v[170:173], v234 offset:20480
	ds_read_b128 v[174:177], v234 offset:21504
	ds_read_b128 v[178:181], v234 offset:22528
	ds_read_b128 v[190:193], v234 offset:23552
	s_add_i32 s58, s58, s24
	v_lshl_add_u64 v[214:215], s[56:57], 0, v[194:195]
	s_mov_b32 m0, s58
	s_nop 0
	global_load_lds_dwordx4 v194, s[56:57]
	s_add_i32 m0, s58, 0x2000
	v_lshl_add_u64 v[216:217], s[56:57], 0, v[204:205]
	s_add_u32 s56, s56, s12
	s_addc_u32 s57, s57, 0
	s_add_i32 s58, s59, s24
	global_load_lds_dwordx4 v[216:217], off
	v_lshl_add_u64 v[218:219], s[56:57], 0, v[194:195]
	s_mov_b32 m0, s58
	v_lshl_add_u64 v[220:221], s[56:57], 0, v[204:205]
	global_load_lds_dwordx4 v194, s[56:57]
	s_add_i32 m0, s58, 0x2000
	s_nop 0
	global_load_lds_dwordx4 v204, s[56:57]
	s_waitcnt vmcnt(6)
	s_waitcnt lgkmcnt(0)
	v_mfma_f32_16x16x32_bf16 v[62:65], v[66:69], v[150:153], 0
	v_mfma_f32_16x16x32_bf16 v[62:65], v[78:81], v[154:157], v[62:65]
	s_barrier
	s_setprio 1
	v_mfma_f32_16x16x32_bf16 v[58:61], v[98:101], v[154:157], 0
	v_mfma_f32_16x16x32_bf16 v[58:61], v[82:85], v[150:153], v[58:61]
	v_mfma_f32_16x16x32_bf16 v[42:45], v[82:85], v[158:161], 0
	v_mfma_f32_16x16x32_bf16 v[42:45], v[98:101], v[162:165], v[42:45]
	v_mfma_f32_16x16x32_bf16 v[46:49], v[78:81], v[162:165], 0
	v_mfma_f32_16x16x32_bf16 v[46:49], v[66:69], v[158:161], v[46:49]
	v_mfma_f32_16x16x32_bf16 v[30:33], v[66:69], v[170:173], 0
	v_mfma_f32_16x16x32_bf16 v[30:33], v[78:81], v[174:177], v[30:33]
	v_mfma_f32_16x16x32_bf16 v[26:29], v[98:101], v[174:177], 0
	v_mfma_f32_16x16x32_bf16 v[26:29], v[82:85], v[170:173], v[26:29]
	v_mfma_f32_16x16x32_bf16 v[10:13], v[82:85], v[178:181], 0
	v_mfma_f32_16x16x32_bf16 v[10:13], v[98:101], v[190:193], v[10:13]
	v_mfma_f32_16x16x32_bf16 v[14:17], v[78:81], v[190:193], 0
	v_mfma_f32_16x16x32_bf16 v[14:17], v[66:69], v[178:181], v[14:17]
	v_mfma_f32_16x16x32_bf16 v[54:57], v[106:109], v[150:153], 0
	v_mfma_f32_16x16x32_bf16 v[54:57], v[118:121], v[154:157], v[54:57]
	v_mfma_f32_16x16x32_bf16 v[50:53], v[142:145], v[154:157], 0
	v_mfma_f32_16x16x32_bf16 v[50:53], v[130:133], v[150:153], v[50:53]
	v_mfma_f32_16x16x32_bf16 v[34:37], v[130:133], v[158:161], 0
	v_mfma_f32_16x16x32_bf16 v[34:37], v[142:145], v[162:165], v[34:37]
	v_mfma_f32_16x16x32_bf16 v[38:41], v[118:121], v[162:165], 0
	v_mfma_f32_16x16x32_bf16 v[38:41], v[106:109], v[158:161], v[38:41]
	v_mfma_f32_16x16x32_bf16 v[22:25], v[106:109], v[170:173], 0
	v_mfma_f32_16x16x32_bf16 v[22:25], v[118:121], v[174:177], v[22:25]
	v_mfma_f32_16x16x32_bf16 v[18:21], v[142:145], v[174:177], 0
	v_mfma_f32_16x16x32_bf16 v[18:21], v[130:133], v[170:173], v[18:21]
	v_mfma_f32_16x16x32_bf16 v[2:5], v[130:133], v[178:181], 0
	v_mfma_f32_16x16x32_bf16 v[2:5], v[142:145], v[190:193], v[2:5]
	v_mfma_f32_16x16x32_bf16 v[6:9], v[118:121], v[190:193], 0
	v_mfma_f32_16x16x32_bf16 v[6:9], v[106:109], v[178:181], v[6:9]
	s_setprio 0
	s_barrier
	s_mov_b32 m0, s26
	s_nop 0
	global_load_lds_dwordx4 v208, s[20:21]
	s_mov_b32 m0, s27
	s_nop 0
	global_load_lds_dwordx4 v206, s[20:21]
	ds_read_b128 v[66:69], v198 offset:32768
	ds_read_b128 v[78:81], v198 offset:33792
	ds_read_b128 v[82:85], v198 offset:34816
	ds_read_b128 v[98:101], v198 offset:35840
	ds_read_b128 v[106:109], v198 offset:49152
	ds_read_b128 v[118:121], v198 offset:50176
	ds_read_b128 v[130:133], v198 offset:51200
	ds_read_b128 v[142:145], v198 offset:52224
	ds_read_b128 v[150:153], v234 offset:32768
	ds_read_b128 v[154:157], v234 offset:33792
	ds_read_b128 v[158:161], v234 offset:34816
	ds_read_b128 v[162:165], v234 offset:35840
	ds_read_b128 v[170:173], v234 offset:36864
	ds_read_b128 v[174:177], v234 offset:37888
	ds_read_b128 v[178:181], v234 offset:38912
	ds_read_b128 v[190:193], v234 offset:39936
	s_add_i32 s56, 0, 0x18000
	s_add_i32 s57, 0, 0x1c000
	s_add_u32 s20, s20, s12
	s_addc_u32 s21, s21, 0
	s_mov_b32 m0, s28
	s_nop 0
	global_load_lds_dwordx4 v208, s[20:21]
	s_mov_b32 m0, s29
	s_nop 0
	global_load_lds_dwordx4 v206, s[20:21]
	s_waitcnt vmcnt(8)
	s_waitcnt lgkmcnt(0)
	v_mfma_f32_16x16x32_bf16 v[186:189], v[66:69], v[150:153], v[186:189]
	v_mfma_f32_16x16x32_bf16 v[186:189], v[78:81], v[154:157], v[186:189]
	s_barrier
	s_setprio 1
	v_mfma_f32_16x16x32_bf16 v[182:185], v[98:101], v[154:157], v[182:185]
	v_mfma_f32_16x16x32_bf16 v[182:185], v[82:85], v[150:153], v[182:185]
	v_mfma_f32_16x16x32_bf16 v[134:137], v[82:85], v[158:161], v[134:137]
	v_mfma_f32_16x16x32_bf16 v[134:137], v[98:101], v[162:165], v[134:137]
	v_mfma_f32_16x16x32_bf16 v[138:141], v[78:81], v[162:165], v[138:141]
	v_mfma_f32_16x16x32_bf16 v[138:141], v[66:69], v[158:161], v[138:141]
	v_mfma_f32_16x16x32_bf16 v[114:117], v[66:69], v[170:173], v[114:117]
	v_mfma_f32_16x16x32_bf16 v[114:117], v[78:81], v[174:177], v[114:117]
	v_mfma_f32_16x16x32_bf16 v[110:113], v[98:101], v[174:177], v[110:113]
	v_mfma_f32_16x16x32_bf16 v[110:113], v[82:85], v[170:173], v[110:113]
	v_mfma_f32_16x16x32_bf16 v[86:89], v[82:85], v[178:181], v[86:89]
	v_mfma_f32_16x16x32_bf16 v[86:89], v[98:101], v[190:193], v[86:89]
	v_mfma_f32_16x16x32_bf16 v[90:93], v[78:81], v[190:193], v[90:93]
	v_mfma_f32_16x16x32_bf16 v[90:93], v[66:69], v[178:181], v[90:93]
	v_mfma_f32_16x16x32_bf16 v[166:169], v[106:109], v[150:153], v[166:169]
	v_mfma_f32_16x16x32_bf16 v[166:169], v[118:121], v[154:157], v[166:169]
	v_mfma_f32_16x16x32_bf16 v[146:149], v[142:145], v[154:157], v[146:149]
	v_mfma_f32_16x16x32_bf16 v[146:149], v[130:133], v[150:153], v[146:149]
	v_mfma_f32_16x16x32_bf16 v[122:125], v[130:133], v[158:161], v[122:125]
	v_mfma_f32_16x16x32_bf16 v[122:125], v[142:145], v[162:165], v[122:125]
	v_mfma_f32_16x16x32_bf16 v[126:129], v[118:121], v[162:165], v[126:129]
	v_mfma_f32_16x16x32_bf16 v[126:129], v[106:109], v[158:161], v[126:129]
	v_mfma_f32_16x16x32_bf16 v[102:105], v[106:109], v[170:173], v[102:105]
	v_mfma_f32_16x16x32_bf16 v[102:105], v[118:121], v[174:177], v[102:105]
	v_mfma_f32_16x16x32_bf16 v[94:97], v[142:145], v[174:177], v[94:97]
	v_mfma_f32_16x16x32_bf16 v[94:97], v[130:133], v[170:173], v[94:97]
	v_mfma_f32_16x16x32_bf16 v[70:73], v[130:133], v[178:181], v[70:73]
	v_mfma_f32_16x16x32_bf16 v[70:73], v[142:145], v[190:193], v[70:73]
	v_mfma_f32_16x16x32_bf16 v[74:77], v[118:121], v[190:193], v[74:77]
	v_mfma_f32_16x16x32_bf16 v[74:77], v[106:109], v[178:181], v[74:77]
	s_setprio 0
	s_barrier
	ds_read_b128 v[150:153], v234 offset:49152
	ds_read_b128 v[154:157], v234 offset:50176
	ds_read_b128 v[158:161], v234 offset:51200
	ds_read_b128 v[162:165], v234 offset:52224
	ds_read_b128 v[170:173], v234 offset:53248
	ds_read_b128 v[174:177], v234 offset:54272
	ds_read_b128 v[178:181], v234 offset:55296
	ds_read_b128 v[190:193], v234 offset:56320
	s_add_i32 s20, s56, s24
	v_lshl_add_u64 v[214:215], v[214:215], 0, s[94:95]
	s_mov_b32 m0, s20
	s_nop 0
	global_load_lds_dwordx4 v[214:215], off
	v_lshl_add_u64 v[214:215], v[216:217], 0, s[94:95]
	s_add_i32 m0, s20, 0x2000
	s_add_i32 s20, s57, s24
	global_load_lds_dwordx4 v[214:215], off
	v_lshl_add_u64 v[214:215], v[218:219], 0, s[94:95]
	s_mov_b32 m0, s20
	s_nop 0
	global_load_lds_dwordx4 v[214:215], off
	v_lshl_add_u64 v[214:215], v[220:221], 0, s[94:95]
	s_add_i32 m0, s20, 0x2000
	s_nop 0
	global_load_lds_dwordx4 v[214:215], off
	s_waitcnt vmcnt(6)
	s_waitcnt lgkmcnt(0)
	v_mfma_f32_16x16x32_bf16 v[62:65], v[66:69], v[150:153], v[62:65]
	v_mfma_f32_16x16x32_bf16 v[62:65], v[78:81], v[154:157], v[62:65]
	s_barrier
	s_setprio 1
	v_mfma_f32_16x16x32_bf16 v[58:61], v[98:101], v[154:157], v[58:61]
	v_mfma_f32_16x16x32_bf16 v[58:61], v[82:85], v[150:153], v[58:61]
	v_mfma_f32_16x16x32_bf16 v[42:45], v[82:85], v[158:161], v[42:45]
	v_mfma_f32_16x16x32_bf16 v[42:45], v[98:101], v[162:165], v[42:45]
	v_mfma_f32_16x16x32_bf16 v[46:49], v[78:81], v[162:165], v[46:49]
	v_mfma_f32_16x16x32_bf16 v[46:49], v[66:69], v[158:161], v[46:49]
	v_mfma_f32_16x16x32_bf16 v[30:33], v[66:69], v[170:173], v[30:33]
	v_mfma_f32_16x16x32_bf16 v[30:33], v[78:81], v[174:177], v[30:33]
	v_mfma_f32_16x16x32_bf16 v[26:29], v[98:101], v[174:177], v[26:29]
	v_mfma_f32_16x16x32_bf16 v[26:29], v[82:85], v[170:173], v[26:29]
	v_mfma_f32_16x16x32_bf16 v[10:13], v[82:85], v[178:181], v[10:13]
	v_mfma_f32_16x16x32_bf16 v[10:13], v[98:101], v[190:193], v[10:13]
	s_add_u32 s18, s18, 0x100
	v_mfma_f32_16x16x32_bf16 v[14:17], v[78:81], v[190:193], v[14:17]
	v_mfma_f32_16x16x32_bf16 v[14:17], v[66:69], v[178:181], v[14:17]
	s_addc_u32 s19, s19, 0
	v_mfma_f32_16x16x32_bf16 v[54:57], v[106:109], v[150:153], v[54:57]
	v_mfma_f32_16x16x32_bf16 v[54:57], v[118:121], v[154:157], v[54:57]
	s_add_u32 s51, s51, 0x100
	v_mfma_f32_16x16x32_bf16 v[50:53], v[142:145], v[154:157], v[50:53]
	v_mfma_f32_16x16x32_bf16 v[50:53], v[130:133], v[150:153], v[50:53]
	s_addc_u32 s54, s54, 0
	v_mfma_f32_16x16x32_bf16 v[34:37], v[130:133], v[158:161], v[34:37]
	v_mfma_f32_16x16x32_bf16 v[34:37], v[142:145], v[162:165], v[34:37]
	s_cmp_ge_u32 s55, s53
	v_mfma_f32_16x16x32_bf16 v[38:41], v[118:121], v[162:165], v[38:41]
	v_mfma_f32_16x16x32_bf16 v[38:41], v[106:109], v[158:161], v[38:41]
	s_mov_b32 s20, s55
	v_mfma_f32_16x16x32_bf16 v[22:25], v[106:109], v[170:173], v[22:25]
	v_mfma_f32_16x16x32_bf16 v[22:25], v[118:121], v[174:177], v[22:25]
	v_mfma_f32_16x16x32_bf16 v[18:21], v[142:145], v[174:177], v[18:21]
	v_mfma_f32_16x16x32_bf16 v[18:21], v[130:133], v[170:173], v[18:21]
	v_mfma_f32_16x16x32_bf16 v[2:5], v[130:133], v[178:181], v[2:5]
	v_mfma_f32_16x16x32_bf16 v[2:5], v[142:145], v[190:193], v[2:5]
	v_mfma_f32_16x16x32_bf16 v[6:9], v[118:121], v[190:193], v[6:9]
	v_mfma_f32_16x16x32_bf16 v[6:9], v[106:109], v[178:181], v[6:9]
	s_setprio 0
	s_barrier
	s_cbranch_scc1 .Lpeel_exit_5
	.p2align	6

.LBB0_873:
	s_ashr_i32 s17, s16, 31
	s_lshl_b64 s[62:63], s[16:17], 7
	s_and_b64 s[6:7], s[6:7], exec
	s_cselect_b32 s23, s62, 0
	s_cselect_b32 s17, s63, 0
	s_add_u32 s6, s18, s23
	s_addc_u32 s7, s19, s17
	s_add_u32 s18, s28, s23
	s_addc_u32 s19, s29, s17
	s_cmp_lt_i32 s25, 1
	s_cbranch_scc1 .LBB0_877
	s_add_i32 s17, s25, -2
	s_add_u32 s20, s20, 0x80
	s_addc_u32 s21, s21, 0
	s_add_u32 s23, s26, 0x100
	s_waitcnt lgkmcnt(0)
	v_mov_b64_e32 v[8:9], v[4:5]
	v_mov_b64_e32 v[20:21], v[4:5]
	v_mov_b64_e32 v[24:25], v[4:5]
	v_mov_b64_e32 v[36:37], v[4:5]
	v_mov_b64_e32 v[40:41], v[4:5]
	v_mov_b64_e32 v[52:53], v[4:5]
	v_mov_b64_e32 v[56:57], v[4:5]
	v_mov_b64_e32 v[12:13], v[4:5]
	v_mov_b64_e32 v[16:17], v[4:5]
	v_mov_b64_e32 v[28:29], v[4:5]
	v_mov_b64_e32 v[32:33], v[4:5]
	v_mov_b64_e32 v[44:45], v[4:5]
	v_mov_b64_e32 v[48:49], v[4:5]
	v_mov_b64_e32 v[60:61], v[4:5]
	v_mov_b64_e32 v[64:65], v[4:5]
	v_mov_b64_e32 v[68:69], v[4:5]
	v_mov_b64_e32 v[72:73], v[4:5]
	v_mov_b64_e32 v[84:85], v[4:5]
	v_mov_b64_e32 v[88:89], v[4:5]
	v_mov_b64_e32 v[100:101], v[4:5]
	v_mov_b64_e32 v[104:105], v[4:5]
	s_waitcnt vmcnt(0)
	v_mov_b64_e32 v[116:117], v[4:5]
	v_mov_b64_e32 v[120:121], v[4:5]
	v_mov_b64_e32 v[76:77], v[4:5]
	v_mov_b64_e32 v[80:81], v[4:5]
	v_mov_b64_e32 v[92:93], v[4:5]
	v_mov_b64_e32 v[96:97], v[4:5]
	v_mov_b64_e32 v[108:109], v[4:5]
	v_mov_b64_e32 v[112:113], v[4:5]
	v_mov_b64_e32 v[124:125], v[4:5]
	v_mov_b64_e32 v[128:129], v[4:5]
	s_addc_u32 s28, s27, 0
	s_mov_b32 s26, 0
	v_mov_b64_e32 v[6:7], v[2:3]
	v_mov_b64_e32 v[18:19], v[2:3]
	v_mov_b64_e32 v[22:23], v[2:3]
	v_mov_b64_e32 v[34:35], v[2:3]
	v_mov_b64_e32 v[38:39], v[2:3]
	v_mov_b64_e32 v[50:51], v[2:3]
	v_mov_b64_e32 v[54:55], v[2:3]
	v_mov_b64_e32 v[10:11], v[2:3]
	v_mov_b64_e32 v[14:15], v[2:3]
	v_mov_b64_e32 v[26:27], v[2:3]
	v_mov_b64_e32 v[30:31], v[2:3]
	v_mov_b64_e32 v[42:43], v[2:3]
	v_mov_b64_e32 v[46:47], v[2:3]
	v_mov_b64_e32 v[58:59], v[2:3]
	v_mov_b64_e32 v[62:63], v[2:3]
	v_mov_b64_e32 v[66:67], v[2:3]
	v_mov_b64_e32 v[70:71], v[2:3]
	v_mov_b64_e32 v[82:83], v[2:3]
	v_mov_b64_e32 v[86:87], v[2:3]
	v_mov_b64_e32 v[98:99], v[2:3]
	v_mov_b64_e32 v[102:103], v[2:3]
	v_mov_b64_e32 v[114:115], v[2:3]
	v_mov_b64_e32 v[118:119], v[2:3]
	v_mov_b64_e32 v[74:75], v[2:3]
	v_mov_b64_e32 v[78:79], v[2:3]
	v_mov_b64_e32 v[90:91], v[2:3]
	v_mov_b64_e32 v[94:95], v[2:3]
	v_mov_b64_e32 v[106:107], v[2:3]
	v_mov_b64_e32 v[110:111], v[2:3]
	v_mov_b64_e32 v[122:123], v[2:3]
	v_mov_b64_e32 v[126:127], v[2:3]
	.p2align	6

.LBB0_972:
	s_ashr_i32 s29, s28, 31
	s_lshl_b64 s[10:11], s[28:29], 20
	s_add_u32 s36, s46, s10
	s_addc_u32 s37, s47, s11
	s_and_b64 s[4:5], s[4:5], exec
	s_cselect_b32 s13, s37, s7
	s_cselect_b32 s29, s36, s6
	s_add_u32 s33, s6, 0x100
	s_addc_u32 s38, s7, 0
	s_mov_b32 s39, -2
	s_add_u32 vcc_lo, s0, 0xffffc000
	s_addc_u32 vcc_hi, s1, -1
	s_mov_b32 m0, s59
	s_nop 0
	global_load_lds_dwordx4 v146, vcc
	s_mov_b32 m0, s60
	s_nop 0
	global_load_lds_dwordx4 v148, vcc
	ds_read_b128 v[130:133], v246
	ds_read_b128 v[134:137], v246 offset:1024
	ds_read_b128 v[150:153], v246 offset:2048
	ds_read_b128 v[154:157], v246 offset:3072
	ds_read_b128 v[158:161], v246 offset:16384
	ds_read_b128 v[162:165], v246 offset:17408
	ds_read_b128 v[166:169], v246 offset:18432
	ds_read_b128 v[170:173], v246 offset:19456
	ds_read_b128 v[174:177], v247
	ds_read_b128 v[178:181], v247 offset:1024
	ds_read_b128 v[182:185], v247 offset:2048
	ds_read_b128 v[186:189], v247 offset:3072
	ds_read_b128 v[190:193], v247 offset:4096
	ds_read_b128 v[204:207], v247 offset:5120
	ds_read_b128 v[208:211], v247 offset:6144
	ds_read_b128 v[212:215], v247 offset:7168
	s_add_u32 s4, s0, 0x100
	s_addc_u32 s5, s1, 0
	s_add_i32 s40, 0, 0x10000
	s_cmp_eq_u32 s39, 28
	s_cselect_b32 s11, s35, s5
	s_cselect_b32 s10, s34, s4
	s_cselect_b32 s7, s13, s38
	s_cselect_b32 s6, s29, s33
	s_add_i32 s41, 0, 0x14000
	s_add_i32 m0, s49, 0xc000
	s_nop 0
	global_load_lds_dwordx4 v146, s[0:1]
	s_add_i32 m0, s49, 0xe000
	s_nop 0
	global_load_lds_dwordx4 v148, s[0:1]
	s_waitcnt vmcnt(16)
	s_waitcnt lgkmcnt(0)
	v_mfma_f32_16x16x32_bf16 v[126:129], v[130:133], v[174:177], 0
	v_mfma_f32_16x16x32_bf16 v[126:129], v[134:137], v[178:181], v[126:129]
	s_barrier
	s_setprio 1
	v_mfma_f32_16x16x32_bf16 v[62:65], v[154:157], v[178:181], 0
	v_mfma_f32_16x16x32_bf16 v[62:65], v[150:153], v[174:177], v[62:65]
	v_mfma_f32_16x16x32_bf16 v[58:61], v[150:153], v[182:185], 0
	v_mfma_f32_16x16x32_bf16 v[58:61], v[154:157], v[186:189], v[58:61]
	v_mfma_f32_16x16x32_bf16 v[122:125], v[134:137], v[186:189], 0
	v_mfma_f32_16x16x32_bf16 v[122:125], v[130:133], v[182:185], v[122:125]
	v_mfma_f32_16x16x32_bf16 v[114:117], v[130:133], v[190:193], 0
	v_mfma_f32_16x16x32_bf16 v[114:117], v[134:137], v[204:207], v[114:117]
	v_mfma_f32_16x16x32_bf16 v[50:53], v[154:157], v[204:207], 0
	v_mfma_f32_16x16x32_bf16 v[50:53], v[150:153], v[190:193], v[50:53]
	v_mfma_f32_16x16x32_bf16 v[42:45], v[150:153], v[208:211], 0
	v_mfma_f32_16x16x32_bf16 v[42:45], v[154:157], v[212:215], v[42:45]
	v_mfma_f32_16x16x32_bf16 v[106:109], v[134:137], v[212:215], 0
	v_mfma_f32_16x16x32_bf16 v[106:109], v[130:133], v[208:211], v[106:109]
	v_mfma_f32_16x16x32_bf16 v[118:121], v[158:161], v[174:177], 0
	v_mfma_f32_16x16x32_bf16 v[118:121], v[162:165], v[178:181], v[118:121]
	v_mfma_f32_16x16x32_bf16 v[54:57], v[170:173], v[178:181], 0
	v_mfma_f32_16x16x32_bf16 v[54:57], v[166:169], v[174:177], v[54:57]
	v_mfma_f32_16x16x32_bf16 v[46:49], v[166:169], v[182:185], 0
	v_mfma_f32_16x16x32_bf16 v[46:49], v[170:173], v[186:189], v[46:49]
	v_mfma_f32_16x16x32_bf16 v[110:113], v[162:165], v[186:189], 0
	v_mfma_f32_16x16x32_bf16 v[110:113], v[158:161], v[182:185], v[110:113]
	v_mfma_f32_16x16x32_bf16 v[102:105], v[158:161], v[190:193], 0
	v_mfma_f32_16x16x32_bf16 v[102:105], v[162:165], v[204:207], v[102:105]
	v_mfma_f32_16x16x32_bf16 v[38:41], v[170:173], v[204:207], 0
	v_mfma_f32_16x16x32_bf16 v[38:41], v[166:169], v[190:193], v[38:41]
	v_mfma_f32_16x16x32_bf16 v[34:37], v[166:169], v[208:211], 0
	v_mfma_f32_16x16x32_bf16 v[34:37], v[170:173], v[212:215], v[34:37]
	v_mfma_f32_16x16x32_bf16 v[98:101], v[162:165], v[212:215], 0
	v_mfma_f32_16x16x32_bf16 v[98:101], v[158:161], v[208:211], v[98:101]
	s_setprio 0
	s_barrier
	ds_read_b128 v[174:177], v247 offset:16384
	ds_read_b128 v[178:181], v247 offset:17408
	ds_read_b128 v[182:185], v247 offset:18432
	ds_read_b128 v[186:189], v247 offset:19456
	ds_read_b128 v[190:193], v247 offset:20480
	ds_read_b128 v[204:207], v247 offset:21504
	ds_read_b128 v[208:211], v247 offset:22528
	ds_read_b128 v[212:215], v247 offset:23552
	s_add_i32 s0, s40, s48
	s_mov_b32 m0, s0
	s_nop 0
	global_load_lds_dwordx4 v140, s[6:7]
	s_add_i32 m0, s0, 0x2000
	s_add_u32 s0, s6, 0x80000
	s_addc_u32 s1, s7, 0
	s_add_i32 s40, s41, s48
	global_load_lds_dwordx4 v144, s[6:7]
	s_mov_b32 m0, s40
	s_nop 0
	global_load_lds_dwordx4 v140, s[0:1]
	s_add_i32 m0, s40, 0x2000
	s_nop 0
	global_load_lds_dwordx4 v144, s[0:1]
	s_waitcnt vmcnt(6)
	s_waitcnt lgkmcnt(0)
	v_mfma_f32_16x16x32_bf16 v[94:97], v[130:133], v[174:177], 0
	v_mfma_f32_16x16x32_bf16 v[94:97], v[134:137], v[178:181], v[94:97]
	s_barrier
	s_setprio 1
	v_mfma_f32_16x16x32_bf16 v[30:33], v[154:157], v[178:181], 0
	v_mfma_f32_16x16x32_bf16 v[30:33], v[150:153], v[174:177], v[30:33]
	v_mfma_f32_16x16x32_bf16 v[26:29], v[150:153], v[182:185], 0
	v_mfma_f32_16x16x32_bf16 v[26:29], v[154:157], v[186:189], v[26:29]
	v_mfma_f32_16x16x32_bf16 v[90:93], v[134:137], v[186:189], 0
	v_mfma_f32_16x16x32_bf16 v[90:93], v[130:133], v[182:185], v[90:93]
	v_mfma_f32_16x16x32_bf16 v[82:85], v[130:133], v[190:193], 0
	v_mfma_f32_16x16x32_bf16 v[82:85], v[134:137], v[204:207], v[82:85]
	v_mfma_f32_16x16x32_bf16 v[18:21], v[154:157], v[204:207], 0
	v_mfma_f32_16x16x32_bf16 v[18:21], v[150:153], v[190:193], v[18:21]
	v_mfma_f32_16x16x32_bf16 v[10:13], v[150:153], v[208:211], 0
	v_mfma_f32_16x16x32_bf16 v[10:13], v[154:157], v[212:215], v[10:13]
	v_mfma_f32_16x16x32_bf16 v[74:77], v[134:137], v[212:215], 0
	v_mfma_f32_16x16x32_bf16 v[74:77], v[130:133], v[208:211], v[74:77]
	v_mfma_f32_16x16x32_bf16 v[86:89], v[158:161], v[174:177], 0
	v_mfma_f32_16x16x32_bf16 v[86:89], v[162:165], v[178:181], v[86:89]
	v_mfma_f32_16x16x32_bf16 v[22:25], v[170:173], v[178:181], 0
	v_mfma_f32_16x16x32_bf16 v[22:25], v[166:169], v[174:177], v[22:25]
	v_mfma_f32_16x16x32_bf16 v[14:17], v[166:169], v[182:185], 0
	v_mfma_f32_16x16x32_bf16 v[14:17], v[170:173], v[186:189], v[14:17]
	v_mfma_f32_16x16x32_bf16 v[78:81], v[162:165], v[186:189], 0
	v_mfma_f32_16x16x32_bf16 v[78:81], v[158:161], v[182:185], v[78:81]
	v_mfma_f32_16x16x32_bf16 v[70:73], v[158:161], v[190:193], 0
	v_mfma_f32_16x16x32_bf16 v[70:73], v[162:165], v[204:207], v[70:73]
	v_mfma_f32_16x16x32_bf16 v[6:9], v[170:173], v[204:207], 0
	v_mfma_f32_16x16x32_bf16 v[6:9], v[166:169], v[190:193], v[6:9]
	v_mfma_f32_16x16x32_bf16 v[2:5], v[166:169], v[208:211], 0
	v_mfma_f32_16x16x32_bf16 v[2:5], v[170:173], v[212:215], v[2:5]
	v_mfma_f32_16x16x32_bf16 v[66:69], v[162:165], v[212:215], 0
	v_mfma_f32_16x16x32_bf16 v[66:69], v[158:161], v[208:211], v[66:69]
	s_setprio 0
	s_barrier
	s_mov_b32 m0, s49
	s_nop 0
	global_load_lds_dwordx4 v138, s[10:11]
	s_mov_b32 m0, s70
	s_nop 0
	global_load_lds_dwordx4 v142, s[10:11]
	ds_read_b128 v[130:133], v246 offset:32768
	ds_read_b128 v[134:137], v246 offset:33792
	ds_read_b128 v[150:153], v246 offset:34816
	ds_read_b128 v[154:157], v246 offset:35840
	ds_read_b128 v[158:161], v246 offset:49152
	ds_read_b128 v[162:165], v246 offset:50176
	ds_read_b128 v[166:169], v246 offset:51200
	ds_read_b128 v[170:173], v246 offset:52224
	ds_read_b128 v[174:177], v247 offset:32768
	ds_read_b128 v[178:181], v247 offset:33792
	ds_read_b128 v[182:185], v247 offset:34816
	ds_read_b128 v[186:189], v247 offset:35840
	ds_read_b128 v[190:193], v247 offset:36864
	ds_read_b128 v[204:207], v247 offset:37888
	ds_read_b128 v[208:211], v247 offset:38912
	ds_read_b128 v[212:215], v247 offset:39936
	s_add_i32 s40, 0, 0x18000
	s_add_i32 s41, 0, 0x1c000
	s_add_u32 s0, s10, 0x4000
	s_addc_u32 s1, s11, 0
	s_mov_b32 m0, s71
	s_nop 0
	global_load_lds_dwordx4 v138, s[0:1]
	s_mov_b32 m0, s73
	s_nop 0
	global_load_lds_dwordx4 v142, s[0:1]
	s_waitcnt vmcnt(8)
	s_waitcnt lgkmcnt(0)
	v_mfma_f32_16x16x32_bf16 v[126:129], v[130:133], v[174:177], v[126:129]
	v_mfma_f32_16x16x32_bf16 v[126:129], v[134:137], v[178:181], v[126:129]
	s_barrier
	s_setprio 1
	v_mfma_f32_16x16x32_bf16 v[62:65], v[154:157], v[178:181], v[62:65]
	v_mfma_f32_16x16x32_bf16 v[62:65], v[150:153], v[174:177], v[62:65]
	v_mfma_f32_16x16x32_bf16 v[58:61], v[150:153], v[182:185], v[58:61]
	v_mfma_f32_16x16x32_bf16 v[58:61], v[154:157], v[186:189], v[58:61]
	v_mfma_f32_16x16x32_bf16 v[122:125], v[134:137], v[186:189], v[122:125]
	v_mfma_f32_16x16x32_bf16 v[122:125], v[130:133], v[182:185], v[122:125]
	v_mfma_f32_16x16x32_bf16 v[114:117], v[130:133], v[190:193], v[114:117]
	v_mfma_f32_16x16x32_bf16 v[114:117], v[134:137], v[204:207], v[114:117]
	v_mfma_f32_16x16x32_bf16 v[50:53], v[154:157], v[204:207], v[50:53]
	v_mfma_f32_16x16x32_bf16 v[50:53], v[150:153], v[190:193], v[50:53]
	v_mfma_f32_16x16x32_bf16 v[42:45], v[150:153], v[208:211], v[42:45]
	v_mfma_f32_16x16x32_bf16 v[42:45], v[154:157], v[212:215], v[42:45]
	v_mfma_f32_16x16x32_bf16 v[106:109], v[134:137], v[212:215], v[106:109]
	v_mfma_f32_16x16x32_bf16 v[106:109], v[130:133], v[208:211], v[106:109]
	v_mfma_f32_16x16x32_bf16 v[118:121], v[158:161], v[174:177], v[118:121]
	v_mfma_f32_16x16x32_bf16 v[118:121], v[162:165], v[178:181], v[118:121]
	v_mfma_f32_16x16x32_bf16 v[54:57], v[170:173], v[178:181], v[54:57]
	v_mfma_f32_16x16x32_bf16 v[54:57], v[166:169], v[174:177], v[54:57]
	v_mfma_f32_16x16x32_bf16 v[46:49], v[166:169], v[182:185], v[46:49]
	v_mfma_f32_16x16x32_bf16 v[46:49], v[170:173], v[186:189], v[46:49]
	v_mfma_f32_16x16x32_bf16 v[110:113], v[162:165], v[186:189], v[110:113]
	v_mfma_f32_16x16x32_bf16 v[110:113], v[158:161], v[182:185], v[110:113]
	v_mfma_f32_16x16x32_bf16 v[102:105], v[158:161], v[190:193], v[102:105]
	v_mfma_f32_16x16x32_bf16 v[102:105], v[162:165], v[204:207], v[102:105]
	v_mfma_f32_16x16x32_bf16 v[38:41], v[170:173], v[204:207], v[38:41]
	v_mfma_f32_16x16x32_bf16 v[38:41], v[166:169], v[190:193], v[38:41]
	v_mfma_f32_16x16x32_bf16 v[34:37], v[166:169], v[208:211], v[34:37]
	v_mfma_f32_16x16x32_bf16 v[34:37], v[170:173], v[212:215], v[34:37]
	v_mfma_f32_16x16x32_bf16 v[98:101], v[162:165], v[212:215], v[98:101]
	v_mfma_f32_16x16x32_bf16 v[98:101], v[158:161], v[208:211], v[98:101]
	s_setprio 0
	s_barrier
	ds_read_b128 v[174:177], v247 offset:49152
	ds_read_b128 v[178:181], v247 offset:50176
	ds_read_b128 v[182:185], v247 offset:51200
	ds_read_b128 v[186:189], v247 offset:52224
	ds_read_b128 v[190:193], v247 offset:53248
	ds_read_b128 v[204:207], v247 offset:54272
	ds_read_b128 v[208:211], v247 offset:55296
	ds_read_b128 v[212:215], v247 offset:56320
	s_add_i32 s0, s40, s48
	s_add_u32 vcc_lo, s6, s94
	s_addc_u32 vcc_hi, s7, s95
	s_mov_b32 m0, s0
	s_nop 0
	global_load_lds_dwordx4 v140, vcc
	s_add_i32 m0, s0, 0x2000
	s_add_u32 s0, s6, 0x80080
	s_addc_u32 s1, s7, 0
	s_add_i32 s6, s41, s48
	global_load_lds_dwordx4 v144, vcc
	s_mov_b32 m0, s6
	s_nop 0
	global_load_lds_dwordx4 v140, s[0:1]
	s_add_i32 m0, s6, 0x2000
	s_nop 0
	global_load_lds_dwordx4 v144, s[0:1]
	s_waitcnt vmcnt(6)
	s_waitcnt lgkmcnt(0)
	v_mfma_f32_16x16x32_bf16 v[94:97], v[130:133], v[174:177], v[94:97]
	v_mfma_f32_16x16x32_bf16 v[94:97], v[134:137], v[178:181], v[94:97]
	s_barrier
	s_setprio 1
	v_mfma_f32_16x16x32_bf16 v[30:33], v[154:157], v[178:181], v[30:33]
	v_mfma_f32_16x16x32_bf16 v[30:33], v[150:153], v[174:177], v[30:33]
	v_mfma_f32_16x16x32_bf16 v[26:29], v[150:153], v[182:185], v[26:29]
	v_mfma_f32_16x16x32_bf16 v[26:29], v[154:157], v[186:189], v[26:29]
	v_mfma_f32_16x16x32_bf16 v[90:93], v[134:137], v[186:189], v[90:93]
	v_mfma_f32_16x16x32_bf16 v[90:93], v[130:133], v[182:185], v[90:93]
	v_mfma_f32_16x16x32_bf16 v[82:85], v[130:133], v[190:193], v[82:85]
	v_mfma_f32_16x16x32_bf16 v[82:85], v[134:137], v[204:207], v[82:85]
	v_mfma_f32_16x16x32_bf16 v[18:21], v[154:157], v[204:207], v[18:21]
	v_mfma_f32_16x16x32_bf16 v[18:21], v[150:153], v[190:193], v[18:21]
	v_mfma_f32_16x16x32_bf16 v[10:13], v[150:153], v[208:211], v[10:13]
	v_mfma_f32_16x16x32_bf16 v[10:13], v[154:157], v[212:215], v[10:13]
	s_add_i32 s39, s39, 2
	v_mfma_f32_16x16x32_bf16 v[74:77], v[134:137], v[212:215], v[74:77]
	v_mfma_f32_16x16x32_bf16 v[74:77], v[130:133], v[208:211], v[74:77]
	s_add_u32 s33, s33, 0x100
	v_mfma_f32_16x16x32_bf16 v[86:89], v[158:161], v[174:177], v[86:89]
	v_mfma_f32_16x16x32_bf16 v[86:89], v[162:165], v[178:181], v[86:89]
	s_addc_u32 s38, s38, 0
	v_mfma_f32_16x16x32_bf16 v[22:25], v[170:173], v[178:181], v[22:25]
	v_mfma_f32_16x16x32_bf16 v[22:25], v[166:169], v[174:177], v[22:25]
	s_cmp_gt_u32 s39, 29
	v_mfma_f32_16x16x32_bf16 v[14:17], v[166:169], v[182:185], v[14:17]
	v_mfma_f32_16x16x32_bf16 v[14:17], v[170:173], v[186:189], v[14:17]
	s_mov_b64 s[0:1], s[4:5]
	v_mfma_f32_16x16x32_bf16 v[78:81], v[162:165], v[186:189], v[78:81]
	v_mfma_f32_16x16x32_bf16 v[78:81], v[158:161], v[182:185], v[78:81]
	v_mfma_f32_16x16x32_bf16 v[70:73], v[158:161], v[190:193], v[70:73]
	v_mfma_f32_16x16x32_bf16 v[70:73], v[162:165], v[204:207], v[70:73]
	v_mfma_f32_16x16x32_bf16 v[6:9], v[170:173], v[204:207], v[6:9]
	v_mfma_f32_16x16x32_bf16 v[6:9], v[166:169], v[190:193], v[6:9]
	v_mfma_f32_16x16x32_bf16 v[2:5], v[166:169], v[208:211], v[2:5]
	v_mfma_f32_16x16x32_bf16 v[2:5], v[170:173], v[212:215], v[2:5]
	v_mfma_f32_16x16x32_bf16 v[66:69], v[162:165], v[212:215], v[66:69]
	v_mfma_f32_16x16x32_bf16 v[66:69], v[158:161], v[208:211], v[66:69]
	s_setprio 0
	s_barrier
	s_cbranch_scc1 .Lpeel_exit_7
	.p2align	6

.LBB0_1440:
	s_add_u32 s46, s20, 0x100
	s_waitcnt lgkmcnt(0)
	s_addc_u32 s47, s21, 0
	s_mov_b32 s48, -2
	s_add_u32 vcc_lo, s18, 0xffea0000
	s_addc_u32 vcc_hi, s19, -1
	s_mov_b32 m0, s38
	s_nop 0
	global_load_lds_dwordx4 v210, vcc
	s_mov_b32 m0, s40
	s_nop 0
	global_load_lds_dwordx4 v212, vcc
	ds_read_b128 v[66:69], v198
	ds_read_b128 v[78:81], v198 offset:1024
	ds_read_b128 v[86:89], v198 offset:2048
	ds_read_b128 v[98:101], v198 offset:3072
	ds_read_b128 v[106:109], v198 offset:16384
	ds_read_b128 v[118:121], v198 offset:17408
	ds_read_b128 v[130:133], v198 offset:18432
	ds_read_b128 v[142:145], v198 offset:19456
	ds_read_b128 v[150:153], v234
	ds_read_b128 v[154:157], v234 offset:1024
	ds_read_b128 v[158:161], v234 offset:2048
	ds_read_b128 v[162:165], v234 offset:3072
	ds_read_b128 v[170:173], v234 offset:4096
	ds_read_b128 v[174:177], v234 offset:5120
	ds_read_b128 v[178:181], v234 offset:6144
	ds_read_b128 v[190:193], v234 offset:7168
	s_add_u32 s20, s18, 0x100
	s_addc_u32 s21, s19, 0
	s_add_i32 s49, 0, 0x10000
	s_cmpk_eq_i32 s48, 0x54
	s_cselect_b32 s25, s1, s21
	s_cselect_b32 s24, s0, s20
	s_cselect_b32 s23, s17, s47
	s_cselect_b32 s22, s16, s46
	s_add_i32 s50, 0, 0x14000
	s_add_i32 m0, s28, 0xc000
	s_nop 0
	global_load_lds_dwordx4 v210, s[18:19]
	s_add_i32 m0, s28, 0xe000
	s_nop 0
	global_load_lds_dwordx4 v212, s[18:19]
	s_waitcnt vmcnt(28)
	s_waitcnt lgkmcnt(0)
	v_mfma_f32_16x16x32_bf16 v[186:189], v[66:69], v[150:153], 0
	v_mfma_f32_16x16x32_bf16 v[186:189], v[78:81], v[154:157], v[186:189]
	s_barrier
	s_setprio 1
	v_mfma_f32_16x16x32_bf16 v[182:185], v[98:101], v[154:157], 0
	v_mfma_f32_16x16x32_bf16 v[182:185], v[86:89], v[150:153], v[182:185]
	v_mfma_f32_16x16x32_bf16 v[134:137], v[86:89], v[158:161], 0
	v_mfma_f32_16x16x32_bf16 v[134:137], v[98:101], v[162:165], v[134:137]
	v_mfma_f32_16x16x32_bf16 v[138:141], v[78:81], v[162:165], 0
	v_mfma_f32_16x16x32_bf16 v[138:141], v[66:69], v[158:161], v[138:141]
	v_mfma_f32_16x16x32_bf16 v[114:117], v[66:69], v[170:173], 0
	v_mfma_f32_16x16x32_bf16 v[114:117], v[78:81], v[174:177], v[114:117]
	v_mfma_f32_16x16x32_bf16 v[110:113], v[98:101], v[174:177], 0
	v_mfma_f32_16x16x32_bf16 v[110:113], v[86:89], v[170:173], v[110:113]
	v_mfma_f32_16x16x32_bf16 v[82:85], v[86:89], v[178:181], 0
	v_mfma_f32_16x16x32_bf16 v[82:85], v[98:101], v[190:193], v[82:85]
	v_mfma_f32_16x16x32_bf16 v[90:93], v[78:81], v[190:193], 0
	v_mfma_f32_16x16x32_bf16 v[90:93], v[66:69], v[178:181], v[90:93]
	v_mfma_f32_16x16x32_bf16 v[166:169], v[106:109], v[150:153], 0
	v_mfma_f32_16x16x32_bf16 v[166:169], v[118:121], v[154:157], v[166:169]
	v_mfma_f32_16x16x32_bf16 v[146:149], v[142:145], v[154:157], 0
	v_mfma_f32_16x16x32_bf16 v[146:149], v[130:133], v[150:153], v[146:149]
	v_mfma_f32_16x16x32_bf16 v[122:125], v[130:133], v[158:161], 0
	v_mfma_f32_16x16x32_bf16 v[122:125], v[142:145], v[162:165], v[122:125]
	v_mfma_f32_16x16x32_bf16 v[126:129], v[118:121], v[162:165], 0
	v_mfma_f32_16x16x32_bf16 v[126:129], v[106:109], v[158:161], v[126:129]
	v_mfma_f32_16x16x32_bf16 v[102:105], v[106:109], v[170:173], 0
	v_mfma_f32_16x16x32_bf16 v[102:105], v[118:121], v[174:177], v[102:105]
	v_mfma_f32_16x16x32_bf16 v[94:97], v[142:145], v[174:177], 0
	v_mfma_f32_16x16x32_bf16 v[94:97], v[130:133], v[170:173], v[94:97]
	v_mfma_f32_16x16x32_bf16 v[70:73], v[130:133], v[178:181], 0
	v_mfma_f32_16x16x32_bf16 v[70:73], v[142:145], v[190:193], v[70:73]
	v_mfma_f32_16x16x32_bf16 v[74:77], v[118:121], v[190:193], 0
	v_mfma_f32_16x16x32_bf16 v[74:77], v[106:109], v[178:181], v[74:77]
	s_setprio 0
	s_barrier
	ds_read_b128 v[150:153], v234 offset:16384
	ds_read_b128 v[154:157], v234 offset:17408
	ds_read_b128 v[158:161], v234 offset:18432
	ds_read_b128 v[162:165], v234 offset:19456
	ds_read_b128 v[170:173], v234 offset:20480
	ds_read_b128 v[174:177], v234 offset:21504
	ds_read_b128 v[178:181], v234 offset:22528
	ds_read_b128 v[190:193], v234 offset:23552
	s_add_i32 s18, s49, s26
	s_mov_b32 m0, s18
	s_nop 0
	global_load_lds_dwordx4 v194, s[22:23]
	s_add_i32 m0, s18, 0x2000
	s_add_u32 s18, s22, 0x160000
	s_addc_u32 s19, s23, 0
	s_add_i32 s49, s50, s26
	global_load_lds_dwordx4 v204, s[22:23]
	s_mov_b32 m0, s49
	s_nop 0
	global_load_lds_dwordx4 v194, s[18:19]
	s_add_i32 m0, s49, 0x2000
	s_nop 0
	global_load_lds_dwordx4 v204, s[18:19]
	s_waitcnt vmcnt(6)
	s_waitcnt lgkmcnt(0)
	v_mfma_f32_16x16x32_bf16 v[62:65], v[66:69], v[150:153], 0
	v_mfma_f32_16x16x32_bf16 v[62:65], v[78:81], v[154:157], v[62:65]
	s_barrier
	s_setprio 1
	v_mfma_f32_16x16x32_bf16 v[58:61], v[98:101], v[154:157], 0
	v_mfma_f32_16x16x32_bf16 v[58:61], v[86:89], v[150:153], v[58:61]
	v_mfma_f32_16x16x32_bf16 v[42:45], v[86:89], v[158:161], 0
	v_mfma_f32_16x16x32_bf16 v[42:45], v[98:101], v[162:165], v[42:45]
	v_mfma_f32_16x16x32_bf16 v[46:49], v[78:81], v[162:165], 0
	v_mfma_f32_16x16x32_bf16 v[46:49], v[66:69], v[158:161], v[46:49]
	v_mfma_f32_16x16x32_bf16 v[30:33], v[66:69], v[170:173], 0
	v_mfma_f32_16x16x32_bf16 v[30:33], v[78:81], v[174:177], v[30:33]
	v_mfma_f32_16x16x32_bf16 v[26:29], v[98:101], v[174:177], 0
	v_mfma_f32_16x16x32_bf16 v[26:29], v[86:89], v[170:173], v[26:29]
	v_mfma_f32_16x16x32_bf16 v[10:13], v[86:89], v[178:181], 0
	v_mfma_f32_16x16x32_bf16 v[10:13], v[98:101], v[190:193], v[10:13]
	v_mfma_f32_16x16x32_bf16 v[14:17], v[78:81], v[190:193], 0
	v_mfma_f32_16x16x32_bf16 v[14:17], v[66:69], v[178:181], v[14:17]
	v_mfma_f32_16x16x32_bf16 v[54:57], v[106:109], v[150:153], 0
	v_mfma_f32_16x16x32_bf16 v[54:57], v[118:121], v[154:157], v[54:57]
	v_mfma_f32_16x16x32_bf16 v[50:53], v[142:145], v[154:157], 0
	v_mfma_f32_16x16x32_bf16 v[50:53], v[130:133], v[150:153], v[50:53]
	v_mfma_f32_16x16x32_bf16 v[34:37], v[130:133], v[158:161], 0
	v_mfma_f32_16x16x32_bf16 v[34:37], v[142:145], v[162:165], v[34:37]
	v_mfma_f32_16x16x32_bf16 v[38:41], v[118:121], v[162:165], 0
	v_mfma_f32_16x16x32_bf16 v[38:41], v[106:109], v[158:161], v[38:41]
	v_mfma_f32_16x16x32_bf16 v[22:25], v[106:109], v[170:173], 0
	v_mfma_f32_16x16x32_bf16 v[22:25], v[118:121], v[174:177], v[22:25]
	v_mfma_f32_16x16x32_bf16 v[18:21], v[142:145], v[174:177], 0
	v_mfma_f32_16x16x32_bf16 v[18:21], v[130:133], v[170:173], v[18:21]
	v_mfma_f32_16x16x32_bf16 v[2:5], v[130:133], v[178:181], 0
	v_mfma_f32_16x16x32_bf16 v[2:5], v[142:145], v[190:193], v[2:5]
	v_mfma_f32_16x16x32_bf16 v[6:9], v[118:121], v[190:193], 0
	v_mfma_f32_16x16x32_bf16 v[6:9], v[106:109], v[178:181], v[6:9]
	s_setprio 0
	s_barrier
	s_mov_b32 m0, s28
	s_nop 0
	global_load_lds_dwordx4 v208, s[24:25]
	s_mov_b32 m0, s29
	s_nop 0
	global_load_lds_dwordx4 v206, s[24:25]
	ds_read_b128 v[66:69], v198 offset:32768
	ds_read_b128 v[78:81], v198 offset:33792
	ds_read_b128 v[86:89], v198 offset:34816
	ds_read_b128 v[98:101], v198 offset:35840
	ds_read_b128 v[106:109], v198 offset:49152
	ds_read_b128 v[118:121], v198 offset:50176
	ds_read_b128 v[130:133], v198 offset:51200
	ds_read_b128 v[142:145], v198 offset:52224
	ds_read_b128 v[150:153], v234 offset:32768
	ds_read_b128 v[154:157], v234 offset:33792
	ds_read_b128 v[158:161], v234 offset:34816
	ds_read_b128 v[162:165], v234 offset:35840
	ds_read_b128 v[170:173], v234 offset:36864
	ds_read_b128 v[174:177], v234 offset:37888
	ds_read_b128 v[178:181], v234 offset:38912
	ds_read_b128 v[190:193], v234 offset:39936
	s_add_i32 s49, 0, 0x18000
	s_add_i32 s50, 0, 0x1c000
	s_add_u32 s18, s24, 0x160000
	s_addc_u32 s19, s25, 0
	s_mov_b32 m0, s33
	s_nop 0
	global_load_lds_dwordx4 v208, s[18:19]
	s_mov_b32 m0, s37
	s_nop 0
	global_load_lds_dwordx4 v206, s[18:19]
	s_waitcnt vmcnt(8)
	s_waitcnt lgkmcnt(0)
	v_mfma_f32_16x16x32_bf16 v[186:189], v[66:69], v[150:153], v[186:189]
	v_mfma_f32_16x16x32_bf16 v[186:189], v[78:81], v[154:157], v[186:189]
	s_barrier
	s_setprio 1
	v_mfma_f32_16x16x32_bf16 v[182:185], v[98:101], v[154:157], v[182:185]
	v_mfma_f32_16x16x32_bf16 v[182:185], v[86:89], v[150:153], v[182:185]
	v_mfma_f32_16x16x32_bf16 v[134:137], v[86:89], v[158:161], v[134:137]
	v_mfma_f32_16x16x32_bf16 v[134:137], v[98:101], v[162:165], v[134:137]
	v_mfma_f32_16x16x32_bf16 v[138:141], v[78:81], v[162:165], v[138:141]
	v_mfma_f32_16x16x32_bf16 v[138:141], v[66:69], v[158:161], v[138:141]
	v_mfma_f32_16x16x32_bf16 v[114:117], v[66:69], v[170:173], v[114:117]
	v_mfma_f32_16x16x32_bf16 v[114:117], v[78:81], v[174:177], v[114:117]
	v_mfma_f32_16x16x32_bf16 v[110:113], v[98:101], v[174:177], v[110:113]
	v_mfma_f32_16x16x32_bf16 v[110:113], v[86:89], v[170:173], v[110:113]
	v_mfma_f32_16x16x32_bf16 v[82:85], v[86:89], v[178:181], v[82:85]
	v_mfma_f32_16x16x32_bf16 v[82:85], v[98:101], v[190:193], v[82:85]
	v_mfma_f32_16x16x32_bf16 v[90:93], v[78:81], v[190:193], v[90:93]
	v_mfma_f32_16x16x32_bf16 v[90:93], v[66:69], v[178:181], v[90:93]
	v_mfma_f32_16x16x32_bf16 v[166:169], v[106:109], v[150:153], v[166:169]
	v_mfma_f32_16x16x32_bf16 v[166:169], v[118:121], v[154:157], v[166:169]
	v_mfma_f32_16x16x32_bf16 v[146:149], v[142:145], v[154:157], v[146:149]
	v_mfma_f32_16x16x32_bf16 v[146:149], v[130:133], v[150:153], v[146:149]
	v_mfma_f32_16x16x32_bf16 v[122:125], v[130:133], v[158:161], v[122:125]
	v_mfma_f32_16x16x32_bf16 v[122:125], v[142:145], v[162:165], v[122:125]
	v_mfma_f32_16x16x32_bf16 v[126:129], v[118:121], v[162:165], v[126:129]
	v_mfma_f32_16x16x32_bf16 v[126:129], v[106:109], v[158:161], v[126:129]
	v_mfma_f32_16x16x32_bf16 v[102:105], v[106:109], v[170:173], v[102:105]
	v_mfma_f32_16x16x32_bf16 v[102:105], v[118:121], v[174:177], v[102:105]
	v_mfma_f32_16x16x32_bf16 v[94:97], v[142:145], v[174:177], v[94:97]
	v_mfma_f32_16x16x32_bf16 v[94:97], v[130:133], v[170:173], v[94:97]
	v_mfma_f32_16x16x32_bf16 v[70:73], v[130:133], v[178:181], v[70:73]
	v_mfma_f32_16x16x32_bf16 v[70:73], v[142:145], v[190:193], v[70:73]
	v_mfma_f32_16x16x32_bf16 v[74:77], v[118:121], v[190:193], v[74:77]
	v_mfma_f32_16x16x32_bf16 v[74:77], v[106:109], v[178:181], v[74:77]
	s_setprio 0
	s_barrier
	ds_read_b128 v[150:153], v234 offset:49152
	ds_read_b128 v[154:157], v234 offset:50176
	ds_read_b128 v[158:161], v234 offset:51200
	ds_read_b128 v[162:165], v234 offset:52224
	ds_read_b128 v[170:173], v234 offset:53248
	ds_read_b128 v[174:177], v234 offset:54272
	ds_read_b128 v[178:181], v234 offset:55296
	ds_read_b128 v[190:193], v234 offset:56320
	s_add_i32 s18, s49, s26
	s_add_u32 vcc_lo, s22, s94
	s_addc_u32 vcc_hi, s23, s95
	s_mov_b32 m0, s18
	s_nop 0
	global_load_lds_dwordx4 v194, vcc
	s_add_i32 m0, s18, 0x2000
	s_add_u32 s18, s22, 0x160080
	s_addc_u32 s19, s23, 0
	s_add_i32 s22, s50, s26
	global_load_lds_dwordx4 v204, vcc
	s_mov_b32 m0, s22
	s_nop 0
	global_load_lds_dwordx4 v194, s[18:19]
	s_add_i32 m0, s22, 0x2000
	s_nop 0
	global_load_lds_dwordx4 v204, s[18:19]
	s_waitcnt vmcnt(6)
	s_waitcnt lgkmcnt(0)
	v_mfma_f32_16x16x32_bf16 v[62:65], v[66:69], v[150:153], v[62:65]
	v_mfma_f32_16x16x32_bf16 v[62:65], v[78:81], v[154:157], v[62:65]
	s_barrier
	s_setprio 1
	v_mfma_f32_16x16x32_bf16 v[58:61], v[98:101], v[154:157], v[58:61]
	v_mfma_f32_16x16x32_bf16 v[58:61], v[86:89], v[150:153], v[58:61]
	v_mfma_f32_16x16x32_bf16 v[42:45], v[86:89], v[158:161], v[42:45]
	v_mfma_f32_16x16x32_bf16 v[42:45], v[98:101], v[162:165], v[42:45]
	v_mfma_f32_16x16x32_bf16 v[46:49], v[78:81], v[162:165], v[46:49]
	v_mfma_f32_16x16x32_bf16 v[46:49], v[66:69], v[158:161], v[46:49]
	v_mfma_f32_16x16x32_bf16 v[30:33], v[66:69], v[170:173], v[30:33]
	v_mfma_f32_16x16x32_bf16 v[30:33], v[78:81], v[174:177], v[30:33]
	v_mfma_f32_16x16x32_bf16 v[26:29], v[98:101], v[174:177], v[26:29]
	v_mfma_f32_16x16x32_bf16 v[26:29], v[86:89], v[170:173], v[26:29]
	v_mfma_f32_16x16x32_bf16 v[10:13], v[86:89], v[178:181], v[10:13]
	v_mfma_f32_16x16x32_bf16 v[10:13], v[98:101], v[190:193], v[10:13]
	s_add_i32 s48, s48, 2
	v_mfma_f32_16x16x32_bf16 v[14:17], v[78:81], v[190:193], v[14:17]
	v_mfma_f32_16x16x32_bf16 v[14:17], v[66:69], v[178:181], v[14:17]
	s_add_u32 s46, s46, 0x100
	v_mfma_f32_16x16x32_bf16 v[54:57], v[106:109], v[150:153], v[54:57]
	v_mfma_f32_16x16x32_bf16 v[54:57], v[118:121], v[154:157], v[54:57]
	s_addc_u32 s47, s47, 0
	v_mfma_f32_16x16x32_bf16 v[50:53], v[142:145], v[154:157], v[50:53]
	v_mfma_f32_16x16x32_bf16 v[50:53], v[130:133], v[150:153], v[50:53]
	s_cmpk_gt_u32 s48, 0x55
	v_mfma_f32_16x16x32_bf16 v[34:37], v[130:133], v[158:161], v[34:37]
	v_mfma_f32_16x16x32_bf16 v[34:37], v[142:145], v[162:165], v[34:37]
	s_mov_b64 s[18:19], s[20:21]
	v_mfma_f32_16x16x32_bf16 v[38:41], v[118:121], v[162:165], v[38:41]
	v_mfma_f32_16x16x32_bf16 v[38:41], v[106:109], v[158:161], v[38:41]
	v_mfma_f32_16x16x32_bf16 v[22:25], v[106:109], v[170:173], v[22:25]
	v_mfma_f32_16x16x32_bf16 v[22:25], v[118:121], v[174:177], v[22:25]
	v_mfma_f32_16x16x32_bf16 v[18:21], v[142:145], v[174:177], v[18:21]
	v_mfma_f32_16x16x32_bf16 v[18:21], v[130:133], v[170:173], v[18:21]
	v_mfma_f32_16x16x32_bf16 v[2:5], v[130:133], v[178:181], v[2:5]
	v_mfma_f32_16x16x32_bf16 v[2:5], v[142:145], v[190:193], v[2:5]
	v_mfma_f32_16x16x32_bf16 v[6:9], v[118:121], v[190:193], v[6:9]
	v_mfma_f32_16x16x32_bf16 v[6:9], v[106:109], v[178:181], v[6:9]
	s_setprio 0
	s_barrier
	s_cbranch_scc1 .Lpeel_exit_8
	.p2align	6

.LBB0_1509:
	s_ashr_i32 s15, s14, 31
	s_lshl_b64 s[28:29], s[14:15], 7
	s_and_b64 s[6:7], s[6:7], exec
	s_cselect_b32 s23, s28, 0
	s_cselect_b32 s15, s29, 0
	s_add_u32 s6, s16, s23
	s_addc_u32 s7, s17, s15
	s_add_u32 s16, s26, s23
	s_addc_u32 s17, s27, s15
	s_cmp_lt_i32 s21, 1
	s_cbranch_scc1 .LBB0_1532
	s_add_i32 s15, s21, -2
	s_add_u32 s23, s24, 0x100
	s_waitcnt lgkmcnt(0)
	v_mov_b64_e32 v[8:9], v[4:5]
	v_mov_b64_e32 v[20:21], v[4:5]
	v_mov_b64_e32 v[24:25], v[4:5]
	v_mov_b64_e32 v[36:37], v[4:5]
	v_mov_b64_e32 v[40:41], v[4:5]
	v_mov_b64_e32 v[52:53], v[4:5]
	v_mov_b64_e32 v[56:57], v[4:5]
	v_mov_b64_e32 v[12:13], v[4:5]
	v_mov_b64_e32 v[16:17], v[4:5]
	v_mov_b64_e32 v[28:29], v[4:5]
	v_mov_b64_e32 v[32:33], v[4:5]
	v_mov_b64_e32 v[44:45], v[4:5]
	v_mov_b64_e32 v[48:49], v[4:5]
	v_mov_b64_e32 v[60:61], v[4:5]
	v_mov_b64_e32 v[64:65], v[4:5]
	v_mov_b64_e32 v[68:69], v[4:5]
	v_mov_b64_e32 v[72:73], v[4:5]
	v_mov_b64_e32 v[84:85], v[4:5]
	v_mov_b64_e32 v[88:89], v[4:5]
	v_mov_b64_e32 v[100:101], v[4:5]
	v_mov_b64_e32 v[104:105], v[4:5]
	v_mov_b64_e32 v[116:117], v[4:5]
	v_mov_b64_e32 v[120:121], v[4:5]
	v_mov_b64_e32 v[76:77], v[4:5]
	v_mov_b64_e32 v[80:81], v[4:5]
	v_mov_b64_e32 v[92:93], v[4:5]
	v_mov_b64_e32 v[96:97], v[4:5]
	v_mov_b64_e32 v[108:109], v[4:5]
	v_mov_b64_e32 v[112:113], v[4:5]
	v_mov_b64_e32 v[124:125], v[4:5]
	v_mov_b64_e32 v[128:129], v[4:5]
	s_addc_u32 s54, s25, 0
	s_mov_b32 s26, 0
	v_mov_b64_e32 v[6:7], v[2:3]
	v_mov_b64_e32 v[18:19], v[2:3]
	v_mov_b64_e32 v[22:23], v[2:3]
	v_mov_b64_e32 v[34:35], v[2:3]
	v_mov_b64_e32 v[38:39], v[2:3]
	v_mov_b64_e32 v[50:51], v[2:3]
	v_mov_b64_e32 v[54:55], v[2:3]
	v_mov_b64_e32 v[10:11], v[2:3]
	v_mov_b64_e32 v[14:15], v[2:3]
	v_mov_b64_e32 v[26:27], v[2:3]
	v_mov_b64_e32 v[30:31], v[2:3]
	v_mov_b64_e32 v[42:43], v[2:3]
	v_mov_b64_e32 v[46:47], v[2:3]
	v_mov_b64_e32 v[58:59], v[2:3]
	v_mov_b64_e32 v[62:63], v[2:3]
	v_mov_b64_e32 v[66:67], v[2:3]
	v_mov_b64_e32 v[70:71], v[2:3]
	v_mov_b64_e32 v[82:83], v[2:3]
	v_mov_b64_e32 v[86:87], v[2:3]
	v_mov_b64_e32 v[98:99], v[2:3]
	v_mov_b64_e32 v[102:103], v[2:3]
	v_mov_b64_e32 v[114:115], v[2:3]
	v_mov_b64_e32 v[118:119], v[2:3]
	v_mov_b64_e32 v[74:75], v[2:3]
	v_mov_b64_e32 v[78:79], v[2:3]
	v_mov_b64_e32 v[90:91], v[2:3]
	v_mov_b64_e32 v[94:95], v[2:3]
	v_mov_b64_e32 v[106:107], v[2:3]
	v_mov_b64_e32 v[110:111], v[2:3]
	v_mov_b64_e32 v[122:123], v[2:3]
	v_mov_b64_e32 v[126:127], v[2:3]
	.p2align	6
